# combo1 + GEMM K-loops: load segments at setprio 1, MFMA segments at setprio 0
# speedup vs baseline: 1.0217x; 1.0039x over previous
; #define PG8_STAGE(bufoff, gbase, voff) do { _Pragma("unroll") for (int _i = 0; _i < 2; ++_i) \
;         __builtin_amdgcn_global_load_lds((const unsigned*)((const char*)(gbase) + (voff)[_i]), (PG8_LAS unsigned*)(lds + (bufoff) + ldsw + _i * 8192), 16, 0, 0); } while (0)
; #define PG8_LDA(dst, b, h) do { _Pragma("unroll") for (int m = 0; m < 4; ++m) _Pragma("unroll") for (int k = 0; k < 2; ++k) dst[m][k] = *(const PG8_LAS bf16x8*)(lds + PG8_SA(b, h) + aoff + m * 2048 + k * 1024); } while (0)
; #define PG8_LDB(dst, b, h) do { _Pragma("unroll") for (int n = 0; n < 2; ++n) _Pragma("unroll") for (int k = 0; k < 2; ++k) dst[n][k] = *(const PG8_LAS bf16x8*)(lds + PG8_SB(b, h) + boff + n * 2048 + k * 1024); } while (0)
; #define PG8_MMA(ai, bj, At, Bt) do { __builtin_amdgcn_s_setprio(1); _Pragma("unroll") for (int m = 0; m < 4; ++m) _Pragma("unroll") for (int n = 0; n < 2; ++n) _Pragma("unroll") for (int k = 0; k < 2; ++k) \
;         acc[ai][bj][m][n] = __builtin_amdgcn_mfma_f32_16x16x32_bf16(Bt[n][k], At[m][k], acc[ai][bj][m][n], 0, 0, 0); __builtin_amdgcn_s_setprio(0); } while (0)
; #define PG8_WAIT_V(n) asm volatile("s_waitcnt vmcnt(" #n ")" ::: "memory")
; #define PG8_WAIT_L(n) asm volatile("s_waitcnt lgkmcnt(" #n ")" ::: "memory")
; #define PG8_BAR __builtin_amdgcn_s_barrier()
; #define PG8_SCHED __builtin_amdgcn_sched_barrier(0)
; template <class Epi, class Sched, bool ALIGN_EPI = false, bool SP2 = false>
; __device__ __forceinline__ void gemm_phase(PG8_LAS unsigned char* lds, const Gemm g, const Sched& S, const Epi& E) {
;     ...
;             PG8_LDB(B0, 0, 0); PG8_LDB(B1, 0, 1); PG8_SCHED; PG8_LDA(At, 0, 0); PG8_STAGE(PG8_SA(1, 1), a1 + hstep, voffA);
;             PG8_WAIT_V(8); PG8_WAIT_L(0); PG8_BAR; PG8_MMA(0, 0, At, B0); PG8_MMA(0, 1, At, B1); PG8_BAR; PG8_SCHED;
;             PG8_LDA(At, 0, 1); PG8_STAGE(PG8_SB(0, 0), b2, voffB); PG8_STAGE(PG8_SB(0, 1), b2 + hstep, voffB); PG8_STAGE(PG8_SA(0, 0), a2, voffA);
;             PG8_WAIT_V(8); PG8_WAIT_L(0); PG8_BAR; PG8_MMA(1, 0, At, B0); PG8_MMA(1, 1, At, B1); PG8_BAR; PG8_SCHED;
.LBB0_100:
	s_setprio 1
	s_add_u32 s28, s8, 0xfffc0080
	s_addc_u32 s29, s9, -1
	s_add_i32 s53, 0, 0x10000
	s_cmp_eq_u32 s45, 12
	s_cselect_b32 s31, s3, s29
	s_cselect_b32 s30, s7, s28
	s_cselect_b32 s29, s11, s44
	s_cselect_b32 s28, s21, s23
	s_add_i32 s56, 0, 0x14000
	v_add_u32_e32 v144, s53, v204
	v_add_u32_e32 v160, s56, v204
	ds_read_b128 v[132:135], v144
	ds_read_b128 v[136:139], v144 offset:1024
	ds_read_b128 v[140:143], v144 offset:2048
	ds_read_b128 v[144:147], v144 offset:3072
	ds_read_b128 v[148:151], v160
	ds_read_b128 v[152:155], v160 offset:1024
	ds_read_b128 v[156:159], v160 offset:2048
	ds_read_b128 v[160:163], v160 offset:3072
	v_lshl_add_u64 v[194:195], s[8:9], 0, v[178:179]
	s_add_i32 m0, s42, 0xc000
	ds_read_b128 v[164:167], v205
	ds_read_b128 v[182:185], v205 offset:1024
	ds_read_b128 v[186:189], v205 offset:2048
	ds_read_b128 v[190:193], v205 offset:3072
	ds_read_b128 v[208:211], v205 offset:4096
	ds_read_b128 v[212:215], v205 offset:5120
	ds_read_b128 v[216:219], v205 offset:6144
	ds_read_b128 v[220:223], v205 offset:7168
	global_load_lds_dwordx4 v[194:195], off
	v_lshl_add_u64 v[194:195], s[8:9], 0, v[180:181]
	s_add_i32 m0, s42, 0xe000
	s_nop 0
	global_load_lds_dwordx4 v[194:195], off
	s_waitcnt vmcnt(8)
	s_waitcnt lgkmcnt(0)
	s_setprio 0
	s_barrier
	s_waitcnt lgkmcnt(0)
	v_mfma_f32_16x16x32_bf16 v[128:131], v[132:135], v[164:167], v[128:131]
	v_mfma_f32_16x16x32_bf16 v[124:127], v[140:143], v[164:167], v[124:127]
	v_mfma_f32_16x16x32_bf16 v[112:115], v[132:135], v[186:189], v[112:115]
	v_mfma_f32_16x16x32_bf16 v[108:111], v[140:143], v[186:189], v[108:111]
	v_mfma_f32_16x16x32_bf16 v[96:99], v[132:135], v[208:211], v[96:99]
	v_mfma_f32_16x16x32_bf16 v[92:95], v[140:143], v[208:211], v[92:95]
	v_mfma_f32_16x16x32_bf16 v[80:83], v[132:135], v[216:219], v[80:83]
	v_mfma_f32_16x16x32_bf16 v[76:79], v[140:143], v[216:219], v[76:79]
	v_mfma_f32_16x16x32_bf16 v[128:131], v[136:139], v[182:185], v[128:131]
	v_mfma_f32_16x16x32_bf16 v[124:127], v[144:147], v[182:185], v[124:127]
	v_mfma_f32_16x16x32_bf16 v[112:115], v[136:139], v[190:193], v[112:115]
	v_mfma_f32_16x16x32_bf16 v[108:111], v[144:147], v[190:193], v[108:111]
	v_mfma_f32_16x16x32_bf16 v[96:99], v[136:139], v[212:215], v[96:99]
	v_mfma_f32_16x16x32_bf16 v[92:95], v[144:147], v[212:215], v[92:95]
	v_mfma_f32_16x16x32_bf16 v[80:83], v[136:139], v[220:223], v[80:83]
	v_mfma_f32_16x16x32_bf16 v[76:79], v[144:147], v[220:223], v[76:79]
	v_mfma_f32_16x16x32_bf16 v[120:123], v[148:151], v[164:167], v[120:123]
	v_mfma_f32_16x16x32_bf16 v[116:119], v[156:159], v[164:167], v[116:119]
	v_mfma_f32_16x16x32_bf16 v[104:107], v[148:151], v[186:189], v[104:107]
	v_mfma_f32_16x16x32_bf16 v[100:103], v[156:159], v[186:189], v[100:103]
	v_mfma_f32_16x16x32_bf16 v[88:91], v[148:151], v[208:211], v[88:91]
	v_mfma_f32_16x16x32_bf16 v[84:87], v[156:159], v[208:211], v[84:87]
	v_mfma_f32_16x16x32_bf16 v[72:75], v[148:151], v[216:219], v[72:75]
	v_mfma_f32_16x16x32_bf16 v[68:71], v[156:159], v[216:219], v[68:71]
	v_mfma_f32_16x16x32_bf16 v[120:123], v[152:155], v[182:185], v[120:123]
	v_mfma_f32_16x16x32_bf16 v[116:119], v[160:163], v[182:185], v[116:119]
	v_mfma_f32_16x16x32_bf16 v[104:107], v[152:155], v[190:193], v[104:107]
	v_mfma_f32_16x16x32_bf16 v[100:103], v[160:163], v[190:193], v[100:103]
	v_mfma_f32_16x16x32_bf16 v[88:91], v[152:155], v[212:215], v[88:91]
	v_mfma_f32_16x16x32_bf16 v[84:87], v[160:163], v[212:215], v[84:87]
	v_mfma_f32_16x16x32_bf16 v[72:75], v[152:155], v[220:223], v[72:75]
	v_mfma_f32_16x16x32_bf16 v[68:71], v[160:163], v[220:223], v[68:71]
	s_barrier
	s_setprio 1
	s_add_i32 s53, s53, s41
	v_lshl_add_u64 v[194:195], s[28:29], 0, v[168:169]
	s_mov_b32 m0, s53
	ds_read_b128 v[164:167], v205 offset:16384
	ds_read_b128 v[182:185], v205 offset:17408
	ds_read_b128 v[186:189], v205 offset:18432
	ds_read_b128 v[190:193], v205 offset:19456
	ds_read_b128 v[208:211], v205 offset:20480
	ds_read_b128 v[212:215], v205 offset:21504
	ds_read_b128 v[216:219], v205 offset:22528
	ds_read_b128 v[220:223], v205 offset:23552
	global_load_lds_dwordx4 v[194:195], off
	s_add_i32 m0, s53, 0x2000
	s_add_u32 s54, s28, 0x40000
	v_lshl_add_u64 v[202:203], s[28:29], 0, v[172:173]
	s_addc_u32 s55, s29, 0
	s_add_i32 s53, s56, s41
	global_load_lds_dwordx4 v[202:203], off
	v_lshl_add_u64 v[224:225], s[54:55], 0, v[168:169]
	s_mov_b32 m0, s53
	v_lshl_add_u64 v[226:227], s[30:31], 0, v[170:171]
	global_load_lds_dwordx4 v[224:225], off
	v_lshl_add_u64 v[224:225], s[54:55], 0, v[172:173]
	s_add_i32 m0, s53, 0x2000
	s_nop 0
	global_load_lds_dwordx4 v[224:225], off
	v_lshl_add_u64 v[224:225], s[30:31], 0, v[0:1]
	s_mov_b32 m0, s42
	s_nop 0
	global_load_lds_dwordx4 v[224:225], off
	s_mov_b32 m0, s43
	s_nop 0
	global_load_lds_dwordx4 v[226:227], off
	s_waitcnt vmcnt(8)
	s_waitcnt lgkmcnt(0)
	s_setprio 0
	s_barrier
; #define PG8_STAGE(bufoff, gbase, voff) do { _Pragma("unroll") for (int _i = 0; _i < 2; ++_i) \
;         __builtin_amdgcn_global_load_lds((const unsigned*)((const char*)(gbase) + (voff)[_i]), (PG8_LAS unsigned*)(lds + (bufoff) + ldsw + _i * 8192), 16, 0, 0); } while (0)
; #define PG8_LDA(dst, b, h) do { _Pragma("unroll") for (int m = 0; m < 4; ++m) _Pragma("unroll") for (int k = 0; k < 2; ++k) dst[m][k] = *(const PG8_LAS bf16x8*)(lds + PG8_SA(b, h) + aoff + m * 2048 + k * 1024); } while (0)
; #define PG8_LDB(dst, b, h) do { _Pragma("unroll") for (int n = 0; n < 2; ++n) _Pragma("unroll") for (int k = 0; k < 2; ++k) dst[n][k] = *(const PG8_LAS bf16x8*)(lds + PG8_SB(b, h) + boff + n * 2048 + k * 1024); } while (0)
; #define PG8_MMA(ai, bj, At, Bt) do { __builtin_amdgcn_s_setprio(1); _Pragma("unroll") for (int m = 0; m < 4; ++m) _Pragma("unroll") for (int n = 0; n < 2; ++n) _Pragma("unroll") for (int k = 0; k < 2; ++k) \
;         acc[ai][bj][m][n] = __builtin_amdgcn_mfma_f32_16x16x32_bf16(Bt[n][k], At[m][k], acc[ai][bj][m][n], 0, 0, 0); __builtin_amdgcn_s_setprio(0); } while (0)
; #define PG8_WAIT_V(n) asm volatile("s_waitcnt vmcnt(" #n ")" ::: "memory")
; #define PG8_WAIT_L(n) asm volatile("s_waitcnt lgkmcnt(" #n ")" ::: "memory")
; #define PG8_BAR __builtin_amdgcn_s_barrier()
; #define PG8_SCHED __builtin_amdgcn_sched_barrier(0)
; template <class Epi, class Sched, bool ALIGN_EPI = false, bool SP2 = false>
; __device__ __forceinline__ void gemm_phase(PG8_LAS unsigned char* lds, const Gemm g, const Sched& S, const Epi& E) {
;     ...
;             PG8_WAIT_V(8); PG8_WAIT_L(0); PG8_BAR; PG8_MMA(1, 0, At, B0); PG8_MMA(1, 1, At, B1); PG8_BAR; PG8_SCHED;
;             PG8_LDB(B0, 1, 0); PG8_LDB(B1, 1, 1); PG8_SCHED; PG8_LDA(At, 1, 0); PG8_STAGE(PG8_SA(0, 1), a2 + hstep, voffA);
;             PG8_WAIT_V(8); PG8_WAIT_L(0); PG8_BAR; PG8_MMA(0, 0, At, B0); PG8_MMA(0, 1, At, B1); PG8_BAR; PG8_SCHED;
	s_waitcnt lgkmcnt(0)
	v_mfma_f32_16x16x32_bf16 v[64:67], v[132:135], v[164:167], v[64:67]
	v_mfma_f32_16x16x32_bf16 v[60:63], v[140:143], v[164:167], v[60:63]
	v_mfma_f32_16x16x32_bf16 v[48:51], v[132:135], v[186:189], v[48:51]
	v_mfma_f32_16x16x32_bf16 v[44:47], v[140:143], v[186:189], v[44:47]
	v_mfma_f32_16x16x32_bf16 v[32:35], v[132:135], v[208:211], v[32:35]
	v_mfma_f32_16x16x32_bf16 v[28:31], v[140:143], v[208:211], v[28:31]
	v_mfma_f32_16x16x32_bf16 v[16:19], v[132:135], v[216:219], v[16:19]
	v_mfma_f32_16x16x32_bf16 v[12:15], v[140:143], v[216:219], v[12:15]
	v_mfma_f32_16x16x32_bf16 v[64:67], v[136:139], v[182:185], v[64:67]
	v_mfma_f32_16x16x32_bf16 v[60:63], v[144:147], v[182:185], v[60:63]
	v_mfma_f32_16x16x32_bf16 v[48:51], v[136:139], v[190:193], v[48:51]
	v_mfma_f32_16x16x32_bf16 v[44:47], v[144:147], v[190:193], v[44:47]
	v_mfma_f32_16x16x32_bf16 v[32:35], v[136:139], v[212:215], v[32:35]
	v_mfma_f32_16x16x32_bf16 v[28:31], v[144:147], v[212:215], v[28:31]
	v_mfma_f32_16x16x32_bf16 v[16:19], v[136:139], v[220:223], v[16:19]
	v_mfma_f32_16x16x32_bf16 v[12:15], v[144:147], v[220:223], v[12:15]
	v_mfma_f32_16x16x32_bf16 v[56:59], v[148:151], v[164:167], v[56:59]
	v_mfma_f32_16x16x32_bf16 v[52:55], v[156:159], v[164:167], v[52:55]
	v_mfma_f32_16x16x32_bf16 v[40:43], v[148:151], v[186:189], v[40:43]
	v_mfma_f32_16x16x32_bf16 v[36:39], v[156:159], v[186:189], v[36:39]
	v_mfma_f32_16x16x32_bf16 v[24:27], v[148:151], v[208:211], v[24:27]
	v_mfma_f32_16x16x32_bf16 v[20:23], v[156:159], v[208:211], v[20:23]
	v_mfma_f32_16x16x32_bf16 v[8:11], v[148:151], v[216:219], v[8:11]
	v_mfma_f32_16x16x32_bf16 v[4:7], v[156:159], v[216:219], v[4:7]
	v_mfma_f32_16x16x32_bf16 v[56:59], v[152:155], v[182:185], v[56:59]
	v_mfma_f32_16x16x32_bf16 v[52:55], v[160:163], v[182:185], v[52:55]
	v_mfma_f32_16x16x32_bf16 v[40:43], v[152:155], v[190:193], v[40:43]
	v_mfma_f32_16x16x32_bf16 v[36:39], v[160:163], v[190:193], v[36:39]
	v_mfma_f32_16x16x32_bf16 v[24:27], v[152:155], v[212:215], v[24:27]
	v_mfma_f32_16x16x32_bf16 v[20:23], v[160:163], v[212:215], v[20:23]
	v_mfma_f32_16x16x32_bf16 v[8:11], v[152:155], v[220:223], v[8:11]
	v_mfma_f32_16x16x32_bf16 v[4:7], v[160:163], v[220:223], v[4:7]
	s_barrier
	s_setprio 1
	s_add_i32 s53, 0, 0x18000
	s_add_i32 s54, 0, 0x1c000
	v_add_u32_e32 v144, s53, v204
	v_add_u32_e32 v160, s54, v204
	ds_read_b128 v[132:135], v144
	ds_read_b128 v[136:139], v144 offset:1024
	ds_read_b128 v[140:143], v144 offset:2048
	ds_read_b128 v[144:147], v144 offset:3072
	ds_read_b128 v[148:151], v160
	ds_read_b128 v[152:155], v160 offset:1024
	ds_read_b128 v[156:159], v160 offset:2048
	ds_read_b128 v[160:163], v160 offset:3072
	s_add_u32 s30, s30, 0x40000
	s_addc_u32 s31, s31, 0
	s_mov_b32 m0, s46
	v_lshl_add_u64 v[228:229], s[30:31], 0, v[0:1]
	ds_read_b128 v[164:167], v205 offset:32768
	ds_read_b128 v[182:185], v205 offset:33792
	ds_read_b128 v[186:189], v205 offset:34816
	ds_read_b128 v[190:193], v205 offset:35840
	ds_read_b128 v[208:211], v205 offset:36864
	ds_read_b128 v[212:215], v205 offset:37888
	ds_read_b128 v[216:219], v205 offset:38912
	ds_read_b128 v[220:223], v205 offset:39936
	global_load_lds_dwordx4 v[228:229], off
	v_lshl_add_u64 v[228:229], s[30:31], 0, v[170:171]
	s_mov_b32 m0, s47
	s_nop 0
	global_load_lds_dwordx4 v[228:229], off
	s_waitcnt vmcnt(8)
	s_waitcnt lgkmcnt(0)
	s_setprio 0
	s_barrier
	s_waitcnt lgkmcnt(0)
	v_mfma_f32_16x16x32_bf16 v[128:131], v[132:135], v[164:167], v[128:131]
	v_mfma_f32_16x16x32_bf16 v[124:127], v[140:143], v[164:167], v[124:127]
	v_mfma_f32_16x16x32_bf16 v[112:115], v[132:135], v[186:189], v[112:115]
	v_mfma_f32_16x16x32_bf16 v[108:111], v[140:143], v[186:189], v[108:111]
	v_mfma_f32_16x16x32_bf16 v[96:99], v[132:135], v[208:211], v[96:99]
	v_mfma_f32_16x16x32_bf16 v[92:95], v[140:143], v[208:211], v[92:95]
	v_mfma_f32_16x16x32_bf16 v[80:83], v[132:135], v[216:219], v[80:83]
	v_mfma_f32_16x16x32_bf16 v[76:79], v[140:143], v[216:219], v[76:79]
	v_mfma_f32_16x16x32_bf16 v[128:131], v[136:139], v[182:185], v[128:131]
	v_mfma_f32_16x16x32_bf16 v[124:127], v[144:147], v[182:185], v[124:127]
	v_mfma_f32_16x16x32_bf16 v[112:115], v[136:139], v[190:193], v[112:115]
	v_mfma_f32_16x16x32_bf16 v[108:111], v[144:147], v[190:193], v[108:111]
	v_mfma_f32_16x16x32_bf16 v[96:99], v[136:139], v[212:215], v[96:99]
	v_mfma_f32_16x16x32_bf16 v[92:95], v[144:147], v[212:215], v[92:95]
	v_mfma_f32_16x16x32_bf16 v[80:83], v[136:139], v[220:223], v[80:83]
	v_mfma_f32_16x16x32_bf16 v[76:79], v[144:147], v[220:223], v[76:79]
	v_mfma_f32_16x16x32_bf16 v[120:123], v[148:151], v[164:167], v[120:123]
	v_mfma_f32_16x16x32_bf16 v[116:119], v[156:159], v[164:167], v[116:119]
	v_mfma_f32_16x16x32_bf16 v[104:107], v[148:151], v[186:189], v[104:107]
	v_mfma_f32_16x16x32_bf16 v[100:103], v[156:159], v[186:189], v[100:103]
	v_mfma_f32_16x16x32_bf16 v[88:91], v[148:151], v[208:211], v[88:91]
	v_mfma_f32_16x16x32_bf16 v[84:87], v[156:159], v[208:211], v[84:87]
	v_mfma_f32_16x16x32_bf16 v[72:75], v[148:151], v[216:219], v[72:75]
	v_mfma_f32_16x16x32_bf16 v[68:71], v[156:159], v[216:219], v[68:71]
	v_mfma_f32_16x16x32_bf16 v[120:123], v[152:155], v[182:185], v[120:123]
	v_mfma_f32_16x16x32_bf16 v[116:119], v[160:163], v[182:185], v[116:119]
	v_mfma_f32_16x16x32_bf16 v[104:107], v[152:155], v[190:193], v[104:107]
	v_mfma_f32_16x16x32_bf16 v[100:103], v[160:163], v[190:193], v[100:103]
	v_mfma_f32_16x16x32_bf16 v[88:91], v[152:155], v[212:215], v[88:91]
	v_mfma_f32_16x16x32_bf16 v[84:87], v[160:163], v[212:215], v[84:87]
	v_mfma_f32_16x16x32_bf16 v[72:75], v[152:155], v[220:223], v[72:75]
	v_mfma_f32_16x16x32_bf16 v[68:71], v[160:163], v[220:223], v[68:71]
	s_barrier
; #define PG8_STAGE(bufoff, gbase, voff) do { _Pragma("unroll") for (int _i = 0; _i < 2; ++_i) \
;         __builtin_amdgcn_global_load_lds((const unsigned*)((const char*)(gbase) + (voff)[_i]), (PG8_LAS unsigned*)(lds + (bufoff) + ldsw + _i * 8192), 16, 0, 0); } while (0)
; #define PG8_LDA(dst, b, h) do { _Pragma("unroll") for (int m = 0; m < 4; ++m) _Pragma("unroll") for (int k = 0; k < 2; ++k) dst[m][k] = *(const PG8_LAS bf16x8*)(lds + PG8_SA(b, h) + aoff + m * 2048 + k * 1024); } while (0)
; #define PG8_MMA(ai, bj, At, Bt) do { __builtin_amdgcn_s_setprio(1); _Pragma("unroll") for (int m = 0; m < 4; ++m) _Pragma("unroll") for (int n = 0; n < 2; ++n) _Pragma("unroll") for (int k = 0; k < 2; ++k) \
;         acc[ai][bj][m][n] = __builtin_amdgcn_mfma_f32_16x16x32_bf16(Bt[n][k], At[m][k], acc[ai][bj][m][n], 0, 0, 0); __builtin_amdgcn_s_setprio(0); } while (0)
; #define PG8_WAIT_V(n) asm volatile("s_waitcnt vmcnt(" #n ")" ::: "memory")
; #define PG8_WAIT_L(n) asm volatile("s_waitcnt lgkmcnt(" #n ")" ::: "memory")
; #define PG8_BAR __builtin_amdgcn_s_barrier()
; #define PG8_SCHED __builtin_amdgcn_sched_barrier(0)
; template <class Epi, class Sched, bool ALIGN_EPI = false, bool SP2 = false>
; __device__ __forceinline__ void gemm_phase(PG8_LAS unsigned char* lds, const Gemm g, const Sched& S, const Epi& E) {
;     ...
;         for (int t = 0; t < nt; t += 2) {
;     ...
;             PG8_LDA(At, 1, 1); PG8_STAGE(PG8_SB(1, 0), b3, voffB); PG8_STAGE(PG8_SB(1, 1), b3 + hstep, voffB); PG8_STAGE(PG8_SA(1, 0), a3, voffA);
;             PG8_WAIT_V(8); PG8_WAIT_L(0); PG8_BAR; PG8_MMA(1, 0, At, B0); PG8_MMA(1, 1, At, B1); PG8_BAR; PG8_SCHED;
	s_setprio 1
	s_add_i32 s30, s53, s41
	v_lshl_add_u64 v[194:195], v[194:195], 0, s[82:83]
	s_mov_b32 m0, s30
	ds_read_b128 v[164:167], v205 offset:49152
	ds_read_b128 v[182:185], v205 offset:50176
	ds_read_b128 v[186:189], v205 offset:51200
	ds_read_b128 v[190:193], v205 offset:52224
	ds_read_b128 v[208:211], v205 offset:53248
	ds_read_b128 v[212:215], v205 offset:54272
	ds_read_b128 v[216:219], v205 offset:55296
	ds_read_b128 v[220:223], v205 offset:56320
	global_load_lds_dwordx4 v[194:195], off
	s_add_i32 m0, s30, 0x2000
	s_add_u32 s28, s28, 0x40080
	v_lshl_add_u64 v[194:195], v[202:203], 0, s[82:83]
	s_addc_u32 s29, s29, 0
	s_add_i32 s30, s54, s41
	global_load_lds_dwordx4 v[194:195], off
	v_lshl_add_u64 v[194:195], s[28:29], 0, v[168:169]
	s_mov_b32 m0, s30
	s_nop 0
	global_load_lds_dwordx4 v[194:195], off
	v_lshl_add_u64 v[194:195], s[28:29], 0, v[172:173]
	s_add_i32 m0, s30, 0x2000
	s_nop 0
	global_load_lds_dwordx4 v[194:195], off
	v_lshl_add_u64 v[194:195], v[224:225], 0, s[82:83]
	s_mov_b32 m0, s50
	s_nop 0
	global_load_lds_dwordx4 v[194:195], off
	v_lshl_add_u64 v[194:195], v[226:227], 0, s[82:83]
	s_mov_b32 m0, s51
	s_nop 0
	global_load_lds_dwordx4 v[194:195], off
	s_waitcnt vmcnt(8)
	s_waitcnt lgkmcnt(0)
	s_setprio 0
	s_barrier
	s_waitcnt lgkmcnt(0)
	v_mfma_f32_16x16x32_bf16 v[64:67], v[132:135], v[164:167], v[64:67]
	v_mfma_f32_16x16x32_bf16 v[60:63], v[140:143], v[164:167], v[60:63]
	v_mfma_f32_16x16x32_bf16 v[48:51], v[132:135], v[186:189], v[48:51]
	v_mfma_f32_16x16x32_bf16 v[44:47], v[140:143], v[186:189], v[44:47]
	v_mfma_f32_16x16x32_bf16 v[32:35], v[132:135], v[208:211], v[32:35]
	v_mfma_f32_16x16x32_bf16 v[28:31], v[140:143], v[208:211], v[28:31]
	v_mfma_f32_16x16x32_bf16 v[16:19], v[132:135], v[216:219], v[16:19]
	v_mfma_f32_16x16x32_bf16 v[12:15], v[140:143], v[216:219], v[12:15]
	v_mfma_f32_16x16x32_bf16 v[64:67], v[136:139], v[182:185], v[64:67]
	v_mfma_f32_16x16x32_bf16 v[60:63], v[144:147], v[182:185], v[60:63]
	v_mfma_f32_16x16x32_bf16 v[48:51], v[136:139], v[190:193], v[48:51]
	v_mfma_f32_16x16x32_bf16 v[44:47], v[144:147], v[190:193], v[44:47]
	v_mfma_f32_16x16x32_bf16 v[32:35], v[136:139], v[212:215], v[32:35]
	v_mfma_f32_16x16x32_bf16 v[28:31], v[144:147], v[212:215], v[28:31]
	v_mfma_f32_16x16x32_bf16 v[16:19], v[136:139], v[220:223], v[16:19]
	v_mfma_f32_16x16x32_bf16 v[12:15], v[144:147], v[220:223], v[12:15]
	v_mfma_f32_16x16x32_bf16 v[56:59], v[148:151], v[164:167], v[56:59]
	v_mfma_f32_16x16x32_bf16 v[52:55], v[156:159], v[164:167], v[52:55]
	v_mfma_f32_16x16x32_bf16 v[40:43], v[148:151], v[186:189], v[40:43]
	v_mfma_f32_16x16x32_bf16 v[36:39], v[156:159], v[186:189], v[36:39]
	v_mfma_f32_16x16x32_bf16 v[24:27], v[148:151], v[208:211], v[24:27]
	v_mfma_f32_16x16x32_bf16 v[20:23], v[156:159], v[208:211], v[20:23]
	v_mfma_f32_16x16x32_bf16 v[8:11], v[148:151], v[216:219], v[8:11]
	v_mfma_f32_16x16x32_bf16 v[4:7], v[156:159], v[216:219], v[4:7]
	v_mfma_f32_16x16x32_bf16 v[56:59], v[152:155], v[182:185], v[56:59]
	v_mfma_f32_16x16x32_bf16 v[52:55], v[160:163], v[182:185], v[52:55]
	v_mfma_f32_16x16x32_bf16 v[40:43], v[152:155], v[190:193], v[40:43]
	v_mfma_f32_16x16x32_bf16 v[36:39], v[160:163], v[190:193], v[36:39]
	v_mfma_f32_16x16x32_bf16 v[24:27], v[152:155], v[212:215], v[24:27]
	v_mfma_f32_16x16x32_bf16 v[20:23], v[160:163], v[212:215], v[20:23]
	v_mfma_f32_16x16x32_bf16 v[8:11], v[152:155], v[220:223], v[8:11]
	v_mfma_f32_16x16x32_bf16 v[4:7], v[160:163], v[220:223], v[4:7]
	s_barrier
	s_setprio 1
	s_add_i32 s45, s45, 2
	s_add_u32 s8, s8, 0x100
	s_addc_u32 s9, s9, 0
	s_add_u32 s23, s23, 0x100
	s_addc_u32 s44, s44, 0
	s_cmp_gt_u32 s45, 13
	s_cbranch_scc0 .LBB0_100
	s_setprio 0
	s_and_b64 vcc, exec, s[14:15]
	s_cbranch_vccz .LBB0_103
	s_barrier

; #define PG8_STAGE(bufoff, gbase, voff) do { _Pragma("unroll") for (int _i = 0; _i < 2; ++_i) \
;         __builtin_amdgcn_global_load_lds((const unsigned*)((const char*)(gbase) + (voff)[_i]), (PG8_LAS unsigned*)(lds + (bufoff) + ldsw + _i * 8192), 16, 0, 0); } while (0)
; #define PG8_LDA(dst, b, h) do { _Pragma("unroll") for (int m = 0; m < 4; ++m) _Pragma("unroll") for (int k = 0; k < 2; ++k) dst[m][k] = *(const PG8_LAS bf16x8*)(lds + PG8_SA(b, h) + aoff + m * 2048 + k * 1024); } while (0)
; #define PG8_LDB(dst, b, h) do { _Pragma("unroll") for (int n = 0; n < 2; ++n) _Pragma("unroll") for (int k = 0; k < 2; ++k) dst[n][k] = *(const PG8_LAS bf16x8*)(lds + PG8_SB(b, h) + boff + n * 2048 + k * 1024); } while (0)
; #define PG8_MMA(ai, bj, At, Bt) do { __builtin_amdgcn_s_setprio(1); _Pragma("unroll") for (int m = 0; m < 4; ++m) _Pragma("unroll") for (int n = 0; n < 2; ++n) _Pragma("unroll") for (int k = 0; k < 2; ++k) \
;         acc[ai][bj][m][n] = __builtin_amdgcn_mfma_f32_16x16x32_bf16(Bt[n][k], At[m][k], acc[ai][bj][m][n], 0, 0, 0); __builtin_amdgcn_s_setprio(0); } while (0)
; #define PG8_WAIT_V(n) asm volatile("s_waitcnt vmcnt(" #n ")" ::: "memory")
; #define PG8_WAIT_L(n) asm volatile("s_waitcnt lgkmcnt(" #n ")" ::: "memory")
; #define PG8_BAR __builtin_amdgcn_s_barrier()
; #define PG8_SCHED __builtin_amdgcn_sched_barrier(0)
; template <class Epi, class Sched, bool ALIGN_EPI = false, bool SP2 = false>
; __device__ __forceinline__ void gemm_phase(PG8_LAS unsigned char* lds, const Gemm g, const Sched& S, const Epi& E) {
;     ...
;             PG8_LDB(B0, 0, 0); PG8_LDB(B1, 0, 1); PG8_SCHED; PG8_LDA(At, 0, 0); PG8_STAGE(PG8_SA(1, 1), a1 + hstep, voffA);
;             PG8_WAIT_V(8); PG8_WAIT_L(0); PG8_BAR; PG8_MMA(0, 0, At, B0); PG8_MMA(0, 1, At, B1); PG8_BAR; PG8_SCHED;
;             PG8_LDA(At, 0, 1); PG8_STAGE(PG8_SB(0, 0), b2, voffB); PG8_STAGE(PG8_SB(0, 1), b2 + hstep, voffB); PG8_STAGE(PG8_SA(0, 0), a2, voffA);
;             PG8_WAIT_V(8); PG8_WAIT_L(0); PG8_BAR; PG8_MMA(1, 0, At, B0); PG8_MMA(1, 1, At, B1); PG8_BAR; PG8_SCHED;
.LBB0_329:
	s_setprio 1
	s_add_u32 s30, s28, 0xfffc0080
	s_addc_u32 s31, s29, -1
	s_add_i32 s52, 0, 0x10000
	s_cmp_eq_u32 s45, 12
	s_cselect_b32 s35, s3, s31
	s_cselect_b32 s34, s17, s30
	s_cselect_b32 s31, s19, s44
	s_cselect_b32 s30, s25, s27
	s_add_i32 s54, 0, 0x14000
	v_add_u32_e32 v128, s52, v251
	v_add_u32_e32 v156, s54, v251
	ds_read_b128 v[108:111], v128
	ds_read_b128 v[112:115], v128 offset:1024
	ds_read_b128 v[124:127], v128 offset:2048
	ds_read_b128 v[128:131], v128 offset:3072
	ds_read_b128 v[132:135], v156
	ds_read_b128 v[140:143], v156 offset:1024
	ds_read_b128 v[148:151], v156 offset:2048
	ds_read_b128 v[156:159], v156 offset:3072
	v_lshl_add_u64 v[212:213], s[28:29], 0, v[208:209]
	s_add_i32 m0, s42, 0xc000
	ds_read_b128 v[164:167], v253
	ds_read_b128 v[168:171], v253 offset:1024
	ds_read_b128 v[172:175], v253 offset:2048
	ds_read_b128 v[176:179], v253 offset:3072
	ds_read_b128 v[180:183], v253 offset:4096
	ds_read_b128 v[184:187], v253 offset:5120
	ds_read_b128 v[188:191], v253 offset:6144
	ds_read_b128 v[192:195], v253 offset:7168
	global_load_lds_dwordx4 v[212:213], off
	v_lshl_add_u64 v[212:213], s[28:29], 0, v[210:211]
	s_add_i32 m0, s42, 0xe000
	s_nop 0
	global_load_lds_dwordx4 v[212:213], off
	s_waitcnt vmcnt(8)
	s_waitcnt lgkmcnt(0)
	s_setprio 0
	s_barrier
	s_waitcnt lgkmcnt(0)
	v_mfma_f32_16x16x32_bf16 v[160:163], v[108:111], v[164:167], v[160:163]
	v_mfma_f32_16x16x32_bf16 v[152:155], v[124:127], v[164:167], v[152:155]
	v_mfma_f32_16x16x32_bf16 v[120:123], v[108:111], v[172:175], v[120:123]
	v_mfma_f32_16x16x32_bf16 v[116:119], v[124:127], v[172:175], v[116:119]
	v_mfma_f32_16x16x32_bf16 v[96:99], v[108:111], v[180:183], v[96:99]
	v_mfma_f32_16x16x32_bf16 v[92:95], v[124:127], v[180:183], v[92:95]
	v_mfma_f32_16x16x32_bf16 v[80:83], v[108:111], v[188:191], v[80:83]
	v_mfma_f32_16x16x32_bf16 v[76:79], v[124:127], v[188:191], v[76:79]
	v_mfma_f32_16x16x32_bf16 v[160:163], v[112:115], v[168:171], v[160:163]
	v_mfma_f32_16x16x32_bf16 v[152:155], v[128:131], v[168:171], v[152:155]
	v_mfma_f32_16x16x32_bf16 v[120:123], v[112:115], v[176:179], v[120:123]
	v_mfma_f32_16x16x32_bf16 v[116:119], v[128:131], v[176:179], v[116:119]
	v_mfma_f32_16x16x32_bf16 v[96:99], v[112:115], v[184:187], v[96:99]
	v_mfma_f32_16x16x32_bf16 v[92:95], v[128:131], v[184:187], v[92:95]
	v_mfma_f32_16x16x32_bf16 v[80:83], v[112:115], v[192:195], v[80:83]
	v_mfma_f32_16x16x32_bf16 v[76:79], v[128:131], v[192:195], v[76:79]
	v_mfma_f32_16x16x32_bf16 v[144:147], v[132:135], v[164:167], v[144:147]
	v_mfma_f32_16x16x32_bf16 v[136:139], v[148:151], v[164:167], v[136:139]
	v_mfma_f32_16x16x32_bf16 v[104:107], v[132:135], v[172:175], v[104:107]
	v_mfma_f32_16x16x32_bf16 v[100:103], v[148:151], v[172:175], v[100:103]
	v_mfma_f32_16x16x32_bf16 v[88:91], v[132:135], v[180:183], v[88:91]
	v_mfma_f32_16x16x32_bf16 v[84:87], v[148:151], v[180:183], v[84:87]
	v_mfma_f32_16x16x32_bf16 v[72:75], v[132:135], v[188:191], v[72:75]
	v_mfma_f32_16x16x32_bf16 v[68:71], v[148:151], v[188:191], v[68:71]
	v_mfma_f32_16x16x32_bf16 v[144:147], v[140:143], v[168:171], v[144:147]
	v_mfma_f32_16x16x32_bf16 v[136:139], v[156:159], v[168:171], v[136:139]
	v_mfma_f32_16x16x32_bf16 v[104:107], v[140:143], v[176:179], v[104:107]
	v_mfma_f32_16x16x32_bf16 v[100:103], v[156:159], v[176:179], v[100:103]
	v_mfma_f32_16x16x32_bf16 v[88:91], v[140:143], v[184:187], v[88:91]
	v_mfma_f32_16x16x32_bf16 v[84:87], v[156:159], v[184:187], v[84:87]
	v_mfma_f32_16x16x32_bf16 v[72:75], v[140:143], v[192:195], v[72:75]
	v_mfma_f32_16x16x32_bf16 v[68:71], v[156:159], v[192:195], v[68:71]
	s_barrier
	s_setprio 1
	s_add_i32 s52, s52, s41
	v_lshl_add_u64 v[212:213], s[30:31], 0, v[202:203]
	s_mov_b32 m0, s52
	ds_read_b128 v[164:167], v253 offset:16384
	ds_read_b128 v[168:171], v253 offset:17408
	ds_read_b128 v[172:175], v253 offset:18432
	ds_read_b128 v[176:179], v253 offset:19456
	ds_read_b128 v[180:183], v253 offset:20480
	ds_read_b128 v[184:187], v253 offset:21504
	ds_read_b128 v[188:191], v253 offset:22528
	ds_read_b128 v[192:195], v253 offset:23552
	global_load_lds_dwordx4 v[212:213], off
	s_add_i32 m0, s52, 0x2000
	s_add_u32 s52, s30, 0x40000
	v_lshl_add_u64 v[214:215], s[30:31], 0, v[206:207]
	s_addc_u32 s53, s31, 0
	s_add_i32 s54, s54, s41
	global_load_lds_dwordx4 v[214:215], off
	v_lshl_add_u64 v[216:217], s[52:53], 0, v[202:203]
	s_mov_b32 m0, s54
	v_lshl_add_u64 v[218:219], s[34:35], 0, v[204:205]
	global_load_lds_dwordx4 v[216:217], off
	v_lshl_add_u64 v[216:217], s[52:53], 0, v[206:207]
	s_add_i32 m0, s54, 0x2000
	s_nop 0
	global_load_lds_dwordx4 v[216:217], off
	v_lshl_add_u64 v[216:217], s[34:35], 0, v[0:1]
	s_mov_b32 m0, s42
	s_nop 0
	global_load_lds_dwordx4 v[216:217], off
	s_mov_b32 m0, s43
	s_nop 0
	global_load_lds_dwordx4 v[218:219], off
	s_waitcnt vmcnt(8)
	s_waitcnt lgkmcnt(0)
	s_setprio 0
	s_barrier
; #define PG8_STAGE(bufoff, gbase, voff) do { _Pragma("unroll") for (int _i = 0; _i < 2; ++_i) \
;         __builtin_amdgcn_global_load_lds((const unsigned*)((const char*)(gbase) + (voff)[_i]), (PG8_LAS unsigned*)(lds + (bufoff) + ldsw + _i * 8192), 16, 0, 0); } while (0)
; #define PG8_LDA(dst, b, h) do { _Pragma("unroll") for (int m = 0; m < 4; ++m) _Pragma("unroll") for (int k = 0; k < 2; ++k) dst[m][k] = *(const PG8_LAS bf16x8*)(lds + PG8_SA(b, h) + aoff + m * 2048 + k * 1024); } while (0)
; #define PG8_LDB(dst, b, h) do { _Pragma("unroll") for (int n = 0; n < 2; ++n) _Pragma("unroll") for (int k = 0; k < 2; ++k) dst[n][k] = *(const PG8_LAS bf16x8*)(lds + PG8_SB(b, h) + boff + n * 2048 + k * 1024); } while (0)
; #define PG8_MMA(ai, bj, At, Bt) do { __builtin_amdgcn_s_setprio(1); _Pragma("unroll") for (int m = 0; m < 4; ++m) _Pragma("unroll") for (int n = 0; n < 2; ++n) _Pragma("unroll") for (int k = 0; k < 2; ++k) \
;         acc[ai][bj][m][n] = __builtin_amdgcn_mfma_f32_16x16x32_bf16(Bt[n][k], At[m][k], acc[ai][bj][m][n], 0, 0, 0); __builtin_amdgcn_s_setprio(0); } while (0)
; #define PG8_WAIT_V(n) asm volatile("s_waitcnt vmcnt(" #n ")" ::: "memory")
; #define PG8_WAIT_L(n) asm volatile("s_waitcnt lgkmcnt(" #n ")" ::: "memory")
; #define PG8_BAR __builtin_amdgcn_s_barrier()
; #define PG8_SCHED __builtin_amdgcn_sched_barrier(0)
; template <class Epi, class Sched, bool ALIGN_EPI = false, bool SP2 = false>
; __device__ __forceinline__ void gemm_phase(PG8_LAS unsigned char* lds, const Gemm g, const Sched& S, const Epi& E) {
;     ...
;             PG8_WAIT_V(8); PG8_WAIT_L(0); PG8_BAR; PG8_MMA(1, 0, At, B0); PG8_MMA(1, 1, At, B1); PG8_BAR; PG8_SCHED;
;             PG8_LDB(B0, 1, 0); PG8_LDB(B1, 1, 1); PG8_SCHED; PG8_LDA(At, 1, 0); PG8_STAGE(PG8_SA(0, 1), a2 + hstep, voffA);
;             PG8_WAIT_V(8); PG8_WAIT_L(0); PG8_BAR; PG8_MMA(0, 0, At, B0); PG8_MMA(0, 1, At, B1); PG8_BAR; PG8_SCHED;
	s_waitcnt lgkmcnt(0)
	v_mfma_f32_16x16x32_bf16 v[64:67], v[108:111], v[164:167], v[64:67]
	v_mfma_f32_16x16x32_bf16 v[60:63], v[124:127], v[164:167], v[60:63]
	v_mfma_f32_16x16x32_bf16 v[48:51], v[108:111], v[172:175], v[48:51]
	v_mfma_f32_16x16x32_bf16 v[44:47], v[124:127], v[172:175], v[44:47]
	v_mfma_f32_16x16x32_bf16 v[32:35], v[108:111], v[180:183], v[32:35]
	v_mfma_f32_16x16x32_bf16 v[28:31], v[124:127], v[180:183], v[28:31]
	v_mfma_f32_16x16x32_bf16 v[16:19], v[108:111], v[188:191], v[16:19]
	v_mfma_f32_16x16x32_bf16 v[12:15], v[124:127], v[188:191], v[12:15]
	v_mfma_f32_16x16x32_bf16 v[64:67], v[112:115], v[168:171], v[64:67]
	v_mfma_f32_16x16x32_bf16 v[60:63], v[128:131], v[168:171], v[60:63]
	v_mfma_f32_16x16x32_bf16 v[48:51], v[112:115], v[176:179], v[48:51]
	v_mfma_f32_16x16x32_bf16 v[44:47], v[128:131], v[176:179], v[44:47]
	v_mfma_f32_16x16x32_bf16 v[32:35], v[112:115], v[184:187], v[32:35]
	v_mfma_f32_16x16x32_bf16 v[28:31], v[128:131], v[184:187], v[28:31]
	v_mfma_f32_16x16x32_bf16 v[16:19], v[112:115], v[192:195], v[16:19]
	v_mfma_f32_16x16x32_bf16 v[12:15], v[128:131], v[192:195], v[12:15]
	v_mfma_f32_16x16x32_bf16 v[56:59], v[132:135], v[164:167], v[56:59]
	v_mfma_f32_16x16x32_bf16 v[52:55], v[148:151], v[164:167], v[52:55]
	v_mfma_f32_16x16x32_bf16 v[40:43], v[132:135], v[172:175], v[40:43]
	v_mfma_f32_16x16x32_bf16 v[36:39], v[148:151], v[172:175], v[36:39]
	v_mfma_f32_16x16x32_bf16 v[24:27], v[132:135], v[180:183], v[24:27]
	v_mfma_f32_16x16x32_bf16 v[20:23], v[148:151], v[180:183], v[20:23]
	v_mfma_f32_16x16x32_bf16 v[8:11], v[132:135], v[188:191], v[8:11]
	v_mfma_f32_16x16x32_bf16 v[4:7], v[148:151], v[188:191], v[4:7]
	v_mfma_f32_16x16x32_bf16 v[56:59], v[140:143], v[168:171], v[56:59]
	v_mfma_f32_16x16x32_bf16 v[52:55], v[156:159], v[168:171], v[52:55]
	v_mfma_f32_16x16x32_bf16 v[40:43], v[140:143], v[176:179], v[40:43]
	v_mfma_f32_16x16x32_bf16 v[36:39], v[156:159], v[176:179], v[36:39]
	v_mfma_f32_16x16x32_bf16 v[24:27], v[140:143], v[184:187], v[24:27]
	v_mfma_f32_16x16x32_bf16 v[20:23], v[156:159], v[184:187], v[20:23]
	v_mfma_f32_16x16x32_bf16 v[8:11], v[140:143], v[192:195], v[8:11]
	v_mfma_f32_16x16x32_bf16 v[4:7], v[156:159], v[192:195], v[4:7]
	s_barrier
	s_setprio 1
	s_add_i32 s52, 0, 0x18000
	s_add_i32 s53, 0, 0x1c000
	v_add_u32_e32 v128, s52, v251
	v_add_u32_e32 v156, s53, v251
	ds_read_b128 v[108:111], v128
	ds_read_b128 v[112:115], v128 offset:1024
	ds_read_b128 v[124:127], v128 offset:2048
	ds_read_b128 v[128:131], v128 offset:3072
	ds_read_b128 v[132:135], v156
	ds_read_b128 v[140:143], v156 offset:1024
	ds_read_b128 v[148:151], v156 offset:2048
	ds_read_b128 v[156:159], v156 offset:3072
	s_add_u32 s34, s34, 0x40000
	s_addc_u32 s35, s35, 0
	s_mov_b32 m0, s46
	v_lshl_add_u64 v[220:221], s[34:35], 0, v[0:1]
	ds_read_b128 v[164:167], v253 offset:32768
	ds_read_b128 v[168:171], v253 offset:33792
	ds_read_b128 v[172:175], v253 offset:34816
	ds_read_b128 v[176:179], v253 offset:35840
	ds_read_b128 v[180:183], v253 offset:36864
	ds_read_b128 v[184:187], v253 offset:37888
	ds_read_b128 v[188:191], v253 offset:38912
	ds_read_b128 v[192:195], v253 offset:39936
	global_load_lds_dwordx4 v[220:221], off
	v_lshl_add_u64 v[220:221], s[34:35], 0, v[204:205]
	s_mov_b32 m0, s47
	s_nop 0
	global_load_lds_dwordx4 v[220:221], off
	s_waitcnt vmcnt(8)
	s_waitcnt lgkmcnt(0)
	s_setprio 0
	s_barrier
	s_waitcnt lgkmcnt(0)
	v_mfma_f32_16x16x32_bf16 v[160:163], v[108:111], v[164:167], v[160:163]
	v_mfma_f32_16x16x32_bf16 v[152:155], v[124:127], v[164:167], v[152:155]
	v_mfma_f32_16x16x32_bf16 v[120:123], v[108:111], v[172:175], v[120:123]
	v_mfma_f32_16x16x32_bf16 v[116:119], v[124:127], v[172:175], v[116:119]
	v_mfma_f32_16x16x32_bf16 v[96:99], v[108:111], v[180:183], v[96:99]
	v_mfma_f32_16x16x32_bf16 v[92:95], v[124:127], v[180:183], v[92:95]
	v_mfma_f32_16x16x32_bf16 v[80:83], v[108:111], v[188:191], v[80:83]
	v_mfma_f32_16x16x32_bf16 v[76:79], v[124:127], v[188:191], v[76:79]
	v_mfma_f32_16x16x32_bf16 v[160:163], v[112:115], v[168:171], v[160:163]
	v_mfma_f32_16x16x32_bf16 v[152:155], v[128:131], v[168:171], v[152:155]
	v_mfma_f32_16x16x32_bf16 v[120:123], v[112:115], v[176:179], v[120:123]
	v_mfma_f32_16x16x32_bf16 v[116:119], v[128:131], v[176:179], v[116:119]
	v_mfma_f32_16x16x32_bf16 v[96:99], v[112:115], v[184:187], v[96:99]
	v_mfma_f32_16x16x32_bf16 v[92:95], v[128:131], v[184:187], v[92:95]
	v_mfma_f32_16x16x32_bf16 v[80:83], v[112:115], v[192:195], v[80:83]
	v_mfma_f32_16x16x32_bf16 v[76:79], v[128:131], v[192:195], v[76:79]
	v_mfma_f32_16x16x32_bf16 v[144:147], v[132:135], v[164:167], v[144:147]
	v_mfma_f32_16x16x32_bf16 v[136:139], v[148:151], v[164:167], v[136:139]
	v_mfma_f32_16x16x32_bf16 v[104:107], v[132:135], v[172:175], v[104:107]
	v_mfma_f32_16x16x32_bf16 v[100:103], v[148:151], v[172:175], v[100:103]
	v_mfma_f32_16x16x32_bf16 v[88:91], v[132:135], v[180:183], v[88:91]
	v_mfma_f32_16x16x32_bf16 v[84:87], v[148:151], v[180:183], v[84:87]
	v_mfma_f32_16x16x32_bf16 v[72:75], v[132:135], v[188:191], v[72:75]
	v_mfma_f32_16x16x32_bf16 v[68:71], v[148:151], v[188:191], v[68:71]
	v_mfma_f32_16x16x32_bf16 v[144:147], v[140:143], v[168:171], v[144:147]
	v_mfma_f32_16x16x32_bf16 v[136:139], v[156:159], v[168:171], v[136:139]
	v_mfma_f32_16x16x32_bf16 v[104:107], v[140:143], v[176:179], v[104:107]
	v_mfma_f32_16x16x32_bf16 v[100:103], v[156:159], v[176:179], v[100:103]
	v_mfma_f32_16x16x32_bf16 v[88:91], v[140:143], v[184:187], v[88:91]
	v_mfma_f32_16x16x32_bf16 v[84:87], v[156:159], v[184:187], v[84:87]
	v_mfma_f32_16x16x32_bf16 v[72:75], v[140:143], v[192:195], v[72:75]
	v_mfma_f32_16x16x32_bf16 v[68:71], v[156:159], v[192:195], v[68:71]
	s_barrier
; #define PG8_STAGE(bufoff, gbase, voff) do { _Pragma("unroll") for (int _i = 0; _i < 2; ++_i) \
;         __builtin_amdgcn_global_load_lds((const unsigned*)((const char*)(gbase) + (voff)[_i]), (PG8_LAS unsigned*)(lds + (bufoff) + ldsw + _i * 8192), 16, 0, 0); } while (0)
; #define PG8_LDA(dst, b, h) do { _Pragma("unroll") for (int m = 0; m < 4; ++m) _Pragma("unroll") for (int k = 0; k < 2; ++k) dst[m][k] = *(const PG8_LAS bf16x8*)(lds + PG8_SA(b, h) + aoff + m * 2048 + k * 1024); } while (0)
; #define PG8_MMA(ai, bj, At, Bt) do { __builtin_amdgcn_s_setprio(1); _Pragma("unroll") for (int m = 0; m < 4; ++m) _Pragma("unroll") for (int n = 0; n < 2; ++n) _Pragma("unroll") for (int k = 0; k < 2; ++k) \
;         acc[ai][bj][m][n] = __builtin_amdgcn_mfma_f32_16x16x32_bf16(Bt[n][k], At[m][k], acc[ai][bj][m][n], 0, 0, 0); __builtin_amdgcn_s_setprio(0); } while (0)
; #define PG8_WAIT_V(n) asm volatile("s_waitcnt vmcnt(" #n ")" ::: "memory")
; #define PG8_WAIT_L(n) asm volatile("s_waitcnt lgkmcnt(" #n ")" ::: "memory")
; #define PG8_BAR __builtin_amdgcn_s_barrier()
; #define PG8_SCHED __builtin_amdgcn_sched_barrier(0)
; template <class Epi, class Sched, bool ALIGN_EPI = false, bool SP2 = false>
; __device__ __forceinline__ void gemm_phase(PG8_LAS unsigned char* lds, const Gemm g, const Sched& S, const Epi& E) {
;     ...
;         for (int t = 0; t < nt; t += 2) {
;     ...
;             PG8_LDA(At, 1, 1); PG8_STAGE(PG8_SB(1, 0), b3, voffB); PG8_STAGE(PG8_SB(1, 1), b3 + hstep, voffB); PG8_STAGE(PG8_SA(1, 0), a3, voffA);
;             PG8_WAIT_V(8); PG8_WAIT_L(0); PG8_BAR; PG8_MMA(1, 0, At, B0); PG8_MMA(1, 1, At, B1); PG8_BAR; PG8_SCHED;
	s_setprio 1
	s_add_i32 s34, s52, s41
	v_lshl_add_u64 v[212:213], v[212:213], 0, s[82:83]
	s_mov_b32 m0, s34
	ds_read_b128 v[164:167], v253 offset:49152
	ds_read_b128 v[168:171], v253 offset:50176
	ds_read_b128 v[172:175], v253 offset:51200
	ds_read_b128 v[176:179], v253 offset:52224
	ds_read_b128 v[180:183], v253 offset:53248
	ds_read_b128 v[184:187], v253 offset:54272
	ds_read_b128 v[188:191], v253 offset:55296
	ds_read_b128 v[192:195], v253 offset:56320
	global_load_lds_dwordx4 v[212:213], off
	s_add_i32 m0, s34, 0x2000
	s_add_u32 s30, s30, 0x40080
	v_lshl_add_u64 v[212:213], v[214:215], 0, s[82:83]
	s_addc_u32 s31, s31, 0
	s_add_i32 s34, s53, s41
	global_load_lds_dwordx4 v[212:213], off
	v_lshl_add_u64 v[212:213], s[30:31], 0, v[202:203]
	s_mov_b32 m0, s34
	s_nop 0
	global_load_lds_dwordx4 v[212:213], off
	v_lshl_add_u64 v[212:213], s[30:31], 0, v[206:207]
	s_add_i32 m0, s34, 0x2000
	s_nop 0
	global_load_lds_dwordx4 v[212:213], off
	v_lshl_add_u64 v[212:213], v[216:217], 0, s[82:83]
	s_mov_b32 m0, s49
	s_nop 0
	global_load_lds_dwordx4 v[212:213], off
	v_lshl_add_u64 v[212:213], v[218:219], 0, s[82:83]
	s_mov_b32 m0, s50
	s_nop 0
	global_load_lds_dwordx4 v[212:213], off
	s_waitcnt vmcnt(8)
	s_waitcnt lgkmcnt(0)
	s_setprio 0
	s_barrier
	s_waitcnt lgkmcnt(0)
	v_mfma_f32_16x16x32_bf16 v[64:67], v[108:111], v[164:167], v[64:67]
	v_mfma_f32_16x16x32_bf16 v[60:63], v[124:127], v[164:167], v[60:63]
	v_mfma_f32_16x16x32_bf16 v[48:51], v[108:111], v[172:175], v[48:51]
	v_mfma_f32_16x16x32_bf16 v[44:47], v[124:127], v[172:175], v[44:47]
	v_mfma_f32_16x16x32_bf16 v[32:35], v[108:111], v[180:183], v[32:35]
	v_mfma_f32_16x16x32_bf16 v[28:31], v[124:127], v[180:183], v[28:31]
	v_mfma_f32_16x16x32_bf16 v[16:19], v[108:111], v[188:191], v[16:19]
	v_mfma_f32_16x16x32_bf16 v[12:15], v[124:127], v[188:191], v[12:15]
	v_mfma_f32_16x16x32_bf16 v[64:67], v[112:115], v[168:171], v[64:67]
	v_mfma_f32_16x16x32_bf16 v[60:63], v[128:131], v[168:171], v[60:63]
	v_mfma_f32_16x16x32_bf16 v[48:51], v[112:115], v[176:179], v[48:51]
	v_mfma_f32_16x16x32_bf16 v[44:47], v[128:131], v[176:179], v[44:47]
	v_mfma_f32_16x16x32_bf16 v[32:35], v[112:115], v[184:187], v[32:35]
	v_mfma_f32_16x16x32_bf16 v[28:31], v[128:131], v[184:187], v[28:31]
	v_mfma_f32_16x16x32_bf16 v[16:19], v[112:115], v[192:195], v[16:19]
	v_mfma_f32_16x16x32_bf16 v[12:15], v[128:131], v[192:195], v[12:15]
	v_mfma_f32_16x16x32_bf16 v[56:59], v[132:135], v[164:167], v[56:59]
	v_mfma_f32_16x16x32_bf16 v[52:55], v[148:151], v[164:167], v[52:55]
	v_mfma_f32_16x16x32_bf16 v[40:43], v[132:135], v[172:175], v[40:43]
	v_mfma_f32_16x16x32_bf16 v[36:39], v[148:151], v[172:175], v[36:39]
	v_mfma_f32_16x16x32_bf16 v[24:27], v[132:135], v[180:183], v[24:27]
	v_mfma_f32_16x16x32_bf16 v[20:23], v[148:151], v[180:183], v[20:23]
	v_mfma_f32_16x16x32_bf16 v[8:11], v[132:135], v[188:191], v[8:11]
	v_mfma_f32_16x16x32_bf16 v[4:7], v[148:151], v[188:191], v[4:7]
	v_mfma_f32_16x16x32_bf16 v[56:59], v[140:143], v[168:171], v[56:59]
	v_mfma_f32_16x16x32_bf16 v[52:55], v[156:159], v[168:171], v[52:55]
	v_mfma_f32_16x16x32_bf16 v[40:43], v[140:143], v[176:179], v[40:43]
	v_mfma_f32_16x16x32_bf16 v[36:39], v[156:159], v[176:179], v[36:39]
	v_mfma_f32_16x16x32_bf16 v[24:27], v[140:143], v[184:187], v[24:27]
	v_mfma_f32_16x16x32_bf16 v[20:23], v[156:159], v[184:187], v[20:23]
	v_mfma_f32_16x16x32_bf16 v[8:11], v[140:143], v[192:195], v[8:11]
	v_mfma_f32_16x16x32_bf16 v[4:7], v[156:159], v[192:195], v[4:7]
	s_barrier
	s_setprio 1
	s_add_i32 s45, s45, 2
	s_add_u32 s28, s28, 0x100
	s_addc_u32 s29, s29, 0
	s_add_u32 s27, s27, 0x100
	s_addc_u32 s44, s44, 0
	s_cmp_gt_u32 s45, 13
	s_cbranch_scc0 .LBB0_329
	s_setprio 0
	s_and_b64 vcc, exec, s[14:15]
	s_cbranch_vccz .LBB0_332
	s_barrier

; #define PG8_STAGE(bufoff, gbase, voff) do { _Pragma("unroll") for (int _i = 0; _i < 2; ++_i) \
;         __builtin_amdgcn_global_load_lds((const unsigned*)((const char*)(gbase) + (voff)[_i]), (PG8_LAS unsigned*)(lds + (bufoff) + ldsw + _i * 8192), 16, 0, 0); } while (0)
; #define PG8_LDA(dst, b, h) do { _Pragma("unroll") for (int m = 0; m < 4; ++m) _Pragma("unroll") for (int k = 0; k < 2; ++k) dst[m][k] = *(const PG8_LAS bf16x8*)(lds + PG8_SA(b, h) + aoff + m * 2048 + k * 1024); } while (0)
; #define PG8_LDB(dst, b, h) do { _Pragma("unroll") for (int n = 0; n < 2; ++n) _Pragma("unroll") for (int k = 0; k < 2; ++k) dst[n][k] = *(const PG8_LAS bf16x8*)(lds + PG8_SB(b, h) + boff + n * 2048 + k * 1024); } while (0)
; #define PG8_MMA(ai, bj, At, Bt) do { __builtin_amdgcn_s_setprio(1); _Pragma("unroll") for (int m = 0; m < 4; ++m) _Pragma("unroll") for (int n = 0; n < 2; ++n) _Pragma("unroll") for (int k = 0; k < 2; ++k) \
;         acc[ai][bj][m][n] = __builtin_amdgcn_mfma_f32_16x16x32_bf16(Bt[n][k], At[m][k], acc[ai][bj][m][n], 0, 0, 0); __builtin_amdgcn_s_setprio(0); } while (0)
; #define PG8_WAIT_V(n) asm volatile("s_waitcnt vmcnt(" #n ")" ::: "memory")
; #define PG8_WAIT_L(n) asm volatile("s_waitcnt lgkmcnt(" #n ")" ::: "memory")
; #define PG8_BAR __builtin_amdgcn_s_barrier()
; #define PG8_SCHED __builtin_amdgcn_sched_barrier(0)
; template <class Epi, class Sched, bool ALIGN_EPI = false, bool SP2 = false>
; __device__ __forceinline__ void gemm_phase(PG8_LAS unsigned char* lds, const Gemm g, const Sched& S, const Epi& E) {
;     ...
;             PG8_LDB(B0, 0, 0); PG8_LDB(B1, 0, 1); PG8_SCHED; PG8_LDA(At, 0, 0); PG8_STAGE(PG8_SA(1, 1), a1 + hstep, voffA);
;             PG8_WAIT_V(8); PG8_WAIT_L(0); PG8_BAR; PG8_MMA(0, 0, At, B0); PG8_MMA(0, 1, At, B1); PG8_BAR; PG8_SCHED;
;             PG8_LDA(At, 0, 1); PG8_STAGE(PG8_SB(0, 0), b2, voffB); PG8_STAGE(PG8_SB(0, 1), b2 + hstep, voffB); PG8_STAGE(PG8_SA(0, 0), a2, voffA);
;             PG8_WAIT_V(8); PG8_WAIT_L(0); PG8_BAR; PG8_MMA(1, 0, At, B0); PG8_MMA(1, 1, At, B1); PG8_BAR; PG8_SCHED;
.LBB0_405:
	s_setprio 1
	s_add_u32 s24, s8, 0xfffc0080
	s_addc_u32 s25, s9, -1
	s_add_i32 s47, 0, 0x10000
	s_cmp_eq_u32 s46, 12
	s_cselect_b32 s27, s7, s25
	s_cselect_b32 s26, s17, s24
	s_cselect_b32 s25, s19, s45
	s_cselect_b32 s24, s43, s44
	s_add_i32 s50, 0, 0x14000
	v_add_u32_e32 v156, s47, v164
	v_add_u32_e32 v167, s50, v164
	ds_read_b128 v[144:147], v156
	ds_read_b128 v[148:151], v156 offset:1024
	ds_read_b128 v[152:155], v156 offset:2048
	ds_read_b128 v[156:159], v156 offset:3072
	ds_read_b128 v[160:163], v167
	ds_read_b128 v[168:171], v167 offset:1024
	ds_read_b128 v[172:175], v167 offset:2048
	ds_read_b128 v[176:179], v167 offset:3072
	v_lshl_add_u64 v[198:199], s[8:9], 0, v[140:141]
	s_add_i32 m0, s37, 0xc000
	ds_read_b128 v[180:183], v166
	ds_read_b128 v[184:187], v166 offset:1024
	ds_read_b128 v[188:191], v166 offset:2048
	ds_read_b128 v[192:195], v166 offset:3072
	ds_read_b128 v[202:205], v166 offset:4096
	ds_read_b128 v[206:209], v166 offset:5120
	ds_read_b128 v[210:213], v166 offset:6144
	ds_read_b128 v[214:217], v166 offset:7168
	global_load_lds_dwordx4 v[198:199], off
	v_lshl_add_u64 v[198:199], s[8:9], 0, v[142:143]
	s_add_i32 m0, s37, 0xe000
	s_nop 0
	global_load_lds_dwordx4 v[198:199], off
	s_waitcnt vmcnt(8)
	s_waitcnt lgkmcnt(0)
	s_setprio 0
	s_barrier
	s_waitcnt lgkmcnt(0)
	v_mfma_f32_16x16x32_bf16 v[128:131], v[144:147], v[180:183], v[128:131]
	v_mfma_f32_16x16x32_bf16 v[120:123], v[152:155], v[180:183], v[120:123]
	v_mfma_f32_16x16x32_bf16 v[112:115], v[144:147], v[188:191], v[112:115]
	v_mfma_f32_16x16x32_bf16 v[104:107], v[152:155], v[188:191], v[104:107]
	v_mfma_f32_16x16x32_bf16 v[96:99], v[144:147], v[202:205], v[96:99]
	v_mfma_f32_16x16x32_bf16 v[88:91], v[152:155], v[202:205], v[88:91]
	v_mfma_f32_16x16x32_bf16 v[80:83], v[144:147], v[210:213], v[80:83]
	v_mfma_f32_16x16x32_bf16 v[72:75], v[152:155], v[210:213], v[72:75]
	v_mfma_f32_16x16x32_bf16 v[128:131], v[148:151], v[184:187], v[128:131]
	v_mfma_f32_16x16x32_bf16 v[120:123], v[156:159], v[184:187], v[120:123]
	v_mfma_f32_16x16x32_bf16 v[112:115], v[148:151], v[192:195], v[112:115]
	v_mfma_f32_16x16x32_bf16 v[104:107], v[156:159], v[192:195], v[104:107]
	v_mfma_f32_16x16x32_bf16 v[96:99], v[148:151], v[206:209], v[96:99]
	v_mfma_f32_16x16x32_bf16 v[88:91], v[156:159], v[206:209], v[88:91]
	v_mfma_f32_16x16x32_bf16 v[80:83], v[148:151], v[214:217], v[80:83]
	v_mfma_f32_16x16x32_bf16 v[72:75], v[156:159], v[214:217], v[72:75]
	v_mfma_f32_16x16x32_bf16 v[124:127], v[160:163], v[180:183], v[124:127]
	v_mfma_f32_16x16x32_bf16 v[116:119], v[172:175], v[180:183], v[116:119]
	v_mfma_f32_16x16x32_bf16 v[108:111], v[160:163], v[188:191], v[108:111]
	v_mfma_f32_16x16x32_bf16 v[100:103], v[172:175], v[188:191], v[100:103]
	v_mfma_f32_16x16x32_bf16 v[92:95], v[160:163], v[202:205], v[92:95]
	v_mfma_f32_16x16x32_bf16 v[84:87], v[172:175], v[202:205], v[84:87]
	v_mfma_f32_16x16x32_bf16 v[76:79], v[160:163], v[210:213], v[76:79]
	v_mfma_f32_16x16x32_bf16 v[68:71], v[172:175], v[210:213], v[68:71]
	v_mfma_f32_16x16x32_bf16 v[124:127], v[168:171], v[184:187], v[124:127]
	v_mfma_f32_16x16x32_bf16 v[116:119], v[176:179], v[184:187], v[116:119]
	v_mfma_f32_16x16x32_bf16 v[108:111], v[168:171], v[192:195], v[108:111]
	v_mfma_f32_16x16x32_bf16 v[100:103], v[176:179], v[192:195], v[100:103]
	v_mfma_f32_16x16x32_bf16 v[92:95], v[168:171], v[206:209], v[92:95]
	v_mfma_f32_16x16x32_bf16 v[84:87], v[176:179], v[206:209], v[84:87]
	v_mfma_f32_16x16x32_bf16 v[76:79], v[168:171], v[214:217], v[76:79]
	v_mfma_f32_16x16x32_bf16 v[68:71], v[176:179], v[214:217], v[68:71]
	s_barrier
	s_setprio 1
	s_add_i32 s47, s47, s35
	v_lshl_add_u64 v[198:199], s[24:25], 0, v[134:135]
	s_mov_b32 m0, s47
	ds_read_b128 v[180:183], v166 offset:16384
	ds_read_b128 v[184:187], v166 offset:17408
	ds_read_b128 v[188:191], v166 offset:18432
	ds_read_b128 v[192:195], v166 offset:19456
	ds_read_b128 v[202:205], v166 offset:20480
	ds_read_b128 v[206:209], v166 offset:21504
	ds_read_b128 v[210:213], v166 offset:22528
	ds_read_b128 v[214:217], v166 offset:23552
	global_load_lds_dwordx4 v[198:199], off
	s_add_i32 m0, s47, 0x2000
	s_add_u32 s48, s24, 0x40000
	v_lshl_add_u64 v[218:219], s[24:25], 0, v[0:1]
	s_addc_u32 s49, s25, 0
	s_add_i32 s47, s50, s35
	global_load_lds_dwordx4 v[218:219], off
	v_lshl_add_u64 v[220:221], s[48:49], 0, v[134:135]
	s_mov_b32 m0, s47
	v_lshl_add_u64 v[222:223], s[26:27], 0, v[132:133]
	global_load_lds_dwordx4 v[220:221], off
	v_lshl_add_u64 v[220:221], s[48:49], 0, v[0:1]
	s_add_i32 m0, s47, 0x2000
	s_nop 0
	global_load_lds_dwordx4 v[220:221], off
	v_lshl_add_u64 v[220:221], s[26:27], 0, v[136:137]
	s_mov_b32 m0, s37
	s_nop 0
	global_load_lds_dwordx4 v[220:221], off
	s_mov_b32 m0, s38
	s_nop 0
	global_load_lds_dwordx4 v[222:223], off
	s_waitcnt vmcnt(8)
	s_waitcnt lgkmcnt(0)
	s_setprio 0
	s_barrier
; #define PG8_STAGE(bufoff, gbase, voff) do { _Pragma("unroll") for (int _i = 0; _i < 2; ++_i) \
;         __builtin_amdgcn_global_load_lds((const unsigned*)((const char*)(gbase) + (voff)[_i]), (PG8_LAS unsigned*)(lds + (bufoff) + ldsw + _i * 8192), 16, 0, 0); } while (0)
; #define PG8_LDA(dst, b, h) do { _Pragma("unroll") for (int m = 0; m < 4; ++m) _Pragma("unroll") for (int k = 0; k < 2; ++k) dst[m][k] = *(const PG8_LAS bf16x8*)(lds + PG8_SA(b, h) + aoff + m * 2048 + k * 1024); } while (0)
; #define PG8_LDB(dst, b, h) do { _Pragma("unroll") for (int n = 0; n < 2; ++n) _Pragma("unroll") for (int k = 0; k < 2; ++k) dst[n][k] = *(const PG8_LAS bf16x8*)(lds + PG8_SB(b, h) + boff + n * 2048 + k * 1024); } while (0)
; #define PG8_MMA(ai, bj, At, Bt) do { __builtin_amdgcn_s_setprio(1); _Pragma("unroll") for (int m = 0; m < 4; ++m) _Pragma("unroll") for (int n = 0; n < 2; ++n) _Pragma("unroll") for (int k = 0; k < 2; ++k) \
;         acc[ai][bj][m][n] = __builtin_amdgcn_mfma_f32_16x16x32_bf16(Bt[n][k], At[m][k], acc[ai][bj][m][n], 0, 0, 0); __builtin_amdgcn_s_setprio(0); } while (0)
; #define PG8_WAIT_V(n) asm volatile("s_waitcnt vmcnt(" #n ")" ::: "memory")
; #define PG8_WAIT_L(n) asm volatile("s_waitcnt lgkmcnt(" #n ")" ::: "memory")
; #define PG8_BAR __builtin_amdgcn_s_barrier()
; #define PG8_SCHED __builtin_amdgcn_sched_barrier(0)
; template <class Epi, class Sched, bool ALIGN_EPI = false, bool SP2 = false>
; __device__ __forceinline__ void gemm_phase(PG8_LAS unsigned char* lds, const Gemm g, const Sched& S, const Epi& E) {
;     ...
;             PG8_WAIT_V(8); PG8_WAIT_L(0); PG8_BAR; PG8_MMA(1, 0, At, B0); PG8_MMA(1, 1, At, B1); PG8_BAR; PG8_SCHED;
;             PG8_LDB(B0, 1, 0); PG8_LDB(B1, 1, 1); PG8_SCHED; PG8_LDA(At, 1, 0); PG8_STAGE(PG8_SA(0, 1), a2 + hstep, voffA);
;             PG8_WAIT_V(8); PG8_WAIT_L(0); PG8_BAR; PG8_MMA(0, 0, At, B0); PG8_MMA(0, 1, At, B1); PG8_BAR; PG8_SCHED;
	s_waitcnt lgkmcnt(0)
	v_mfma_f32_16x16x32_bf16 v[64:67], v[144:147], v[180:183], v[64:67]
	v_mfma_f32_16x16x32_bf16 v[56:59], v[152:155], v[180:183], v[56:59]
	v_mfma_f32_16x16x32_bf16 v[48:51], v[144:147], v[188:191], v[48:51]
	v_mfma_f32_16x16x32_bf16 v[40:43], v[152:155], v[188:191], v[40:43]
	v_mfma_f32_16x16x32_bf16 v[32:35], v[144:147], v[202:205], v[32:35]
	v_mfma_f32_16x16x32_bf16 v[24:27], v[152:155], v[202:205], v[24:27]
	v_mfma_f32_16x16x32_bf16 v[16:19], v[144:147], v[210:213], v[16:19]
	v_mfma_f32_16x16x32_bf16 v[8:11], v[152:155], v[210:213], v[8:11]
	v_mfma_f32_16x16x32_bf16 v[64:67], v[148:151], v[184:187], v[64:67]
	v_mfma_f32_16x16x32_bf16 v[56:59], v[156:159], v[184:187], v[56:59]
	v_mfma_f32_16x16x32_bf16 v[48:51], v[148:151], v[192:195], v[48:51]
	v_mfma_f32_16x16x32_bf16 v[40:43], v[156:159], v[192:195], v[40:43]
	v_mfma_f32_16x16x32_bf16 v[32:35], v[148:151], v[206:209], v[32:35]
	v_mfma_f32_16x16x32_bf16 v[24:27], v[156:159], v[206:209], v[24:27]
	v_mfma_f32_16x16x32_bf16 v[16:19], v[148:151], v[214:217], v[16:19]
	v_mfma_f32_16x16x32_bf16 v[8:11], v[156:159], v[214:217], v[8:11]
	v_mfma_f32_16x16x32_bf16 v[60:63], v[160:163], v[180:183], v[60:63]
	v_mfma_f32_16x16x32_bf16 v[52:55], v[172:175], v[180:183], v[52:55]
	v_mfma_f32_16x16x32_bf16 v[44:47], v[160:163], v[188:191], v[44:47]
	v_mfma_f32_16x16x32_bf16 v[36:39], v[172:175], v[188:191], v[36:39]
	v_mfma_f32_16x16x32_bf16 v[28:31], v[160:163], v[202:205], v[28:31]
	v_mfma_f32_16x16x32_bf16 v[20:23], v[172:175], v[202:205], v[20:23]
	v_mfma_f32_16x16x32_bf16 v[12:15], v[160:163], v[210:213], v[12:15]
	v_mfma_f32_16x16x32_bf16 v[4:7], v[172:175], v[210:213], v[4:7]
	v_mfma_f32_16x16x32_bf16 v[60:63], v[168:171], v[184:187], v[60:63]
	v_mfma_f32_16x16x32_bf16 v[52:55], v[176:179], v[184:187], v[52:55]
	v_mfma_f32_16x16x32_bf16 v[44:47], v[168:171], v[192:195], v[44:47]
	v_mfma_f32_16x16x32_bf16 v[36:39], v[176:179], v[192:195], v[36:39]
	v_mfma_f32_16x16x32_bf16 v[28:31], v[168:171], v[206:209], v[28:31]
	v_mfma_f32_16x16x32_bf16 v[20:23], v[176:179], v[206:209], v[20:23]
	v_mfma_f32_16x16x32_bf16 v[12:15], v[168:171], v[214:217], v[12:15]
	v_mfma_f32_16x16x32_bf16 v[4:7], v[176:179], v[214:217], v[4:7]
	s_barrier
	s_setprio 1
	s_add_i32 s47, 0, 0x18000
	s_add_i32 s48, 0, 0x1c000
	v_add_u32_e32 v156, s47, v164
	v_add_u32_e32 v167, s48, v164
	ds_read_b128 v[144:147], v156
	ds_read_b128 v[148:151], v156 offset:1024
	ds_read_b128 v[152:155], v156 offset:2048
	ds_read_b128 v[156:159], v156 offset:3072
	ds_read_b128 v[160:163], v167
	ds_read_b128 v[168:171], v167 offset:1024
	ds_read_b128 v[172:175], v167 offset:2048
	ds_read_b128 v[176:179], v167 offset:3072
	s_add_u32 s26, s26, 0x40000
	s_addc_u32 s27, s27, 0
	s_mov_b32 m0, s39
	v_lshl_add_u64 v[224:225], s[26:27], 0, v[136:137]
	ds_read_b128 v[180:183], v166 offset:32768
	ds_read_b128 v[184:187], v166 offset:33792
	ds_read_b128 v[188:191], v166 offset:34816
	ds_read_b128 v[192:195], v166 offset:35840
	ds_read_b128 v[202:205], v166 offset:36864
	ds_read_b128 v[206:209], v166 offset:37888
	ds_read_b128 v[210:213], v166 offset:38912
	ds_read_b128 v[214:217], v166 offset:39936
	global_load_lds_dwordx4 v[224:225], off
	v_lshl_add_u64 v[224:225], s[26:27], 0, v[132:133]
	s_mov_b32 m0, s40
	s_nop 0
	global_load_lds_dwordx4 v[224:225], off
	s_waitcnt vmcnt(8)
	s_waitcnt lgkmcnt(0)
	s_setprio 0
	s_barrier
	s_waitcnt lgkmcnt(0)
	v_mfma_f32_16x16x32_bf16 v[128:131], v[144:147], v[180:183], v[128:131]
	v_mfma_f32_16x16x32_bf16 v[120:123], v[152:155], v[180:183], v[120:123]
	v_mfma_f32_16x16x32_bf16 v[112:115], v[144:147], v[188:191], v[112:115]
	v_mfma_f32_16x16x32_bf16 v[104:107], v[152:155], v[188:191], v[104:107]
	v_mfma_f32_16x16x32_bf16 v[96:99], v[144:147], v[202:205], v[96:99]
	v_mfma_f32_16x16x32_bf16 v[88:91], v[152:155], v[202:205], v[88:91]
	v_mfma_f32_16x16x32_bf16 v[80:83], v[144:147], v[210:213], v[80:83]
	v_mfma_f32_16x16x32_bf16 v[72:75], v[152:155], v[210:213], v[72:75]
	v_mfma_f32_16x16x32_bf16 v[128:131], v[148:151], v[184:187], v[128:131]
	v_mfma_f32_16x16x32_bf16 v[120:123], v[156:159], v[184:187], v[120:123]
	v_mfma_f32_16x16x32_bf16 v[112:115], v[148:151], v[192:195], v[112:115]
	v_mfma_f32_16x16x32_bf16 v[104:107], v[156:159], v[192:195], v[104:107]
	v_mfma_f32_16x16x32_bf16 v[96:99], v[148:151], v[206:209], v[96:99]
	v_mfma_f32_16x16x32_bf16 v[88:91], v[156:159], v[206:209], v[88:91]
	v_mfma_f32_16x16x32_bf16 v[80:83], v[148:151], v[214:217], v[80:83]
	v_mfma_f32_16x16x32_bf16 v[72:75], v[156:159], v[214:217], v[72:75]
	v_mfma_f32_16x16x32_bf16 v[124:127], v[160:163], v[180:183], v[124:127]
	v_mfma_f32_16x16x32_bf16 v[116:119], v[172:175], v[180:183], v[116:119]
	v_mfma_f32_16x16x32_bf16 v[108:111], v[160:163], v[188:191], v[108:111]
	v_mfma_f32_16x16x32_bf16 v[100:103], v[172:175], v[188:191], v[100:103]
	v_mfma_f32_16x16x32_bf16 v[92:95], v[160:163], v[202:205], v[92:95]
	v_mfma_f32_16x16x32_bf16 v[84:87], v[172:175], v[202:205], v[84:87]
	v_mfma_f32_16x16x32_bf16 v[76:79], v[160:163], v[210:213], v[76:79]
	v_mfma_f32_16x16x32_bf16 v[68:71], v[172:175], v[210:213], v[68:71]
	v_mfma_f32_16x16x32_bf16 v[124:127], v[168:171], v[184:187], v[124:127]
	v_mfma_f32_16x16x32_bf16 v[116:119], v[176:179], v[184:187], v[116:119]
	v_mfma_f32_16x16x32_bf16 v[108:111], v[168:171], v[192:195], v[108:111]
	v_mfma_f32_16x16x32_bf16 v[100:103], v[176:179], v[192:195], v[100:103]
	v_mfma_f32_16x16x32_bf16 v[92:95], v[168:171], v[206:209], v[92:95]
	v_mfma_f32_16x16x32_bf16 v[84:87], v[176:179], v[206:209], v[84:87]
	v_mfma_f32_16x16x32_bf16 v[76:79], v[168:171], v[214:217], v[76:79]
	v_mfma_f32_16x16x32_bf16 v[68:71], v[176:179], v[214:217], v[68:71]
	s_barrier
; #define PG8_STAGE(bufoff, gbase, voff) do { _Pragma("unroll") for (int _i = 0; _i < 2; ++_i) \
;         __builtin_amdgcn_global_load_lds((const unsigned*)((const char*)(gbase) + (voff)[_i]), (PG8_LAS unsigned*)(lds + (bufoff) + ldsw + _i * 8192), 16, 0, 0); } while (0)
; #define PG8_LDA(dst, b, h) do { _Pragma("unroll") for (int m = 0; m < 4; ++m) _Pragma("unroll") for (int k = 0; k < 2; ++k) dst[m][k] = *(const PG8_LAS bf16x8*)(lds + PG8_SA(b, h) + aoff + m * 2048 + k * 1024); } while (0)
; #define PG8_MMA(ai, bj, At, Bt) do { __builtin_amdgcn_s_setprio(1); _Pragma("unroll") for (int m = 0; m < 4; ++m) _Pragma("unroll") for (int n = 0; n < 2; ++n) _Pragma("unroll") for (int k = 0; k < 2; ++k) \
;         acc[ai][bj][m][n] = __builtin_amdgcn_mfma_f32_16x16x32_bf16(Bt[n][k], At[m][k], acc[ai][bj][m][n], 0, 0, 0); __builtin_amdgcn_s_setprio(0); } while (0)
; #define PG8_WAIT_V(n) asm volatile("s_waitcnt vmcnt(" #n ")" ::: "memory")
; #define PG8_WAIT_L(n) asm volatile("s_waitcnt lgkmcnt(" #n ")" ::: "memory")
; #define PG8_BAR __builtin_amdgcn_s_barrier()
; #define PG8_SCHED __builtin_amdgcn_sched_barrier(0)
; template <class Epi, class Sched, bool ALIGN_EPI = false, bool SP2 = false>
; __device__ __forceinline__ void gemm_phase(PG8_LAS unsigned char* lds, const Gemm g, const Sched& S, const Epi& E) {
;     ...
;         for (int t = 0; t < nt; t += 2) {
;     ...
;             PG8_LDA(At, 1, 1); PG8_STAGE(PG8_SB(1, 0), b3, voffB); PG8_STAGE(PG8_SB(1, 1), b3 + hstep, voffB); PG8_STAGE(PG8_SA(1, 0), a3, voffA);
;             PG8_WAIT_V(8); PG8_WAIT_L(0); PG8_BAR; PG8_MMA(1, 0, At, B0); PG8_MMA(1, 1, At, B1); PG8_BAR; PG8_SCHED;
	s_setprio 1
	s_add_i32 s26, s47, s35
	v_lshl_add_u64 v[198:199], v[198:199], 0, s[82:83]
	s_mov_b32 m0, s26
	ds_read_b128 v[180:183], v166 offset:49152
	ds_read_b128 v[184:187], v166 offset:50176
	ds_read_b128 v[188:191], v166 offset:51200
	ds_read_b128 v[192:195], v166 offset:52224
	ds_read_b128 v[202:205], v166 offset:53248
	ds_read_b128 v[206:209], v166 offset:54272
	ds_read_b128 v[210:213], v166 offset:55296
	ds_read_b128 v[214:217], v166 offset:56320
	global_load_lds_dwordx4 v[198:199], off
	s_add_i32 m0, s26, 0x2000
	s_add_u32 s24, s24, 0x40080
	v_lshl_add_u64 v[198:199], v[218:219], 0, s[82:83]
	s_addc_u32 s25, s25, 0
	s_add_i32 s26, s48, s35
	global_load_lds_dwordx4 v[198:199], off
	v_lshl_add_u64 v[198:199], s[24:25], 0, v[134:135]
	s_mov_b32 m0, s26
	s_nop 0
	global_load_lds_dwordx4 v[198:199], off
	v_lshl_add_u64 v[198:199], s[24:25], 0, v[0:1]
	s_add_i32 m0, s26, 0x2000
	s_nop 0
	global_load_lds_dwordx4 v[198:199], off
	v_lshl_add_u64 v[198:199], v[220:221], 0, s[82:83]
	s_mov_b32 m0, s41
	s_nop 0
	global_load_lds_dwordx4 v[198:199], off
	v_lshl_add_u64 v[198:199], v[222:223], 0, s[82:83]
	s_mov_b32 m0, s42
	s_nop 0
	global_load_lds_dwordx4 v[198:199], off
	s_waitcnt vmcnt(8)
	s_waitcnt lgkmcnt(0)
	s_setprio 0
	s_barrier
	s_waitcnt lgkmcnt(0)
	v_mfma_f32_16x16x32_bf16 v[64:67], v[144:147], v[180:183], v[64:67]
	v_mfma_f32_16x16x32_bf16 v[56:59], v[152:155], v[180:183], v[56:59]
	v_mfma_f32_16x16x32_bf16 v[48:51], v[144:147], v[188:191], v[48:51]
	v_mfma_f32_16x16x32_bf16 v[40:43], v[152:155], v[188:191], v[40:43]
	v_mfma_f32_16x16x32_bf16 v[32:35], v[144:147], v[202:205], v[32:35]
	v_mfma_f32_16x16x32_bf16 v[24:27], v[152:155], v[202:205], v[24:27]
	v_mfma_f32_16x16x32_bf16 v[16:19], v[144:147], v[210:213], v[16:19]
	v_mfma_f32_16x16x32_bf16 v[8:11], v[152:155], v[210:213], v[8:11]
	v_mfma_f32_16x16x32_bf16 v[64:67], v[148:151], v[184:187], v[64:67]
	v_mfma_f32_16x16x32_bf16 v[56:59], v[156:159], v[184:187], v[56:59]
	v_mfma_f32_16x16x32_bf16 v[48:51], v[148:151], v[192:195], v[48:51]
	v_mfma_f32_16x16x32_bf16 v[40:43], v[156:159], v[192:195], v[40:43]
	v_mfma_f32_16x16x32_bf16 v[32:35], v[148:151], v[206:209], v[32:35]
	v_mfma_f32_16x16x32_bf16 v[24:27], v[156:159], v[206:209], v[24:27]
	v_mfma_f32_16x16x32_bf16 v[16:19], v[148:151], v[214:217], v[16:19]
	v_mfma_f32_16x16x32_bf16 v[8:11], v[156:159], v[214:217], v[8:11]
	v_mfma_f32_16x16x32_bf16 v[60:63], v[160:163], v[180:183], v[60:63]
	v_mfma_f32_16x16x32_bf16 v[52:55], v[172:175], v[180:183], v[52:55]
	v_mfma_f32_16x16x32_bf16 v[44:47], v[160:163], v[188:191], v[44:47]
	v_mfma_f32_16x16x32_bf16 v[36:39], v[172:175], v[188:191], v[36:39]
	v_mfma_f32_16x16x32_bf16 v[28:31], v[160:163], v[202:205], v[28:31]
	v_mfma_f32_16x16x32_bf16 v[20:23], v[172:175], v[202:205], v[20:23]
	v_mfma_f32_16x16x32_bf16 v[12:15], v[160:163], v[210:213], v[12:15]
	v_mfma_f32_16x16x32_bf16 v[4:7], v[172:175], v[210:213], v[4:7]
	v_mfma_f32_16x16x32_bf16 v[60:63], v[168:171], v[184:187], v[60:63]
	v_mfma_f32_16x16x32_bf16 v[52:55], v[176:179], v[184:187], v[52:55]
	v_mfma_f32_16x16x32_bf16 v[44:47], v[168:171], v[192:195], v[44:47]
	v_mfma_f32_16x16x32_bf16 v[36:39], v[176:179], v[192:195], v[36:39]
	v_mfma_f32_16x16x32_bf16 v[28:31], v[168:171], v[206:209], v[28:31]
	v_mfma_f32_16x16x32_bf16 v[20:23], v[176:179], v[206:209], v[20:23]
	v_mfma_f32_16x16x32_bf16 v[12:15], v[168:171], v[214:217], v[12:15]
	v_mfma_f32_16x16x32_bf16 v[4:7], v[176:179], v[214:217], v[4:7]
	s_barrier
	s_setprio 1
	s_add_i32 s46, s46, 2
	s_add_u32 s8, s8, 0x100
	s_addc_u32 s9, s9, 0
	s_add_u32 s44, s44, 0x100
	s_addc_u32 s45, s45, 0
	s_cmp_gt_u32 s46, 13
	s_cbranch_scc0 .LBB0_405
	s_setprio 0
	s_and_b64 vcc, exec, s[14:15]
	s_cbranch_vccz .LBB0_408
	s_barrier

; #define PG8_STAGE(bufoff, gbase, voff) do { _Pragma("unroll") for (int _i = 0; _i < 2; ++_i) \
;         __builtin_amdgcn_global_load_lds((const unsigned*)((const char*)(gbase) + (voff)[_i]), (PG8_LAS unsigned*)(lds + (bufoff) + ldsw + _i * 8192), 16, 0, 0); } while (0)
; #define PG8_LDA(dst, b, h) do { _Pragma("unroll") for (int m = 0; m < 4; ++m) _Pragma("unroll") for (int k = 0; k < 2; ++k) dst[m][k] = *(const PG8_LAS bf16x8*)(lds + PG8_SA(b, h) + aoff + m * 2048 + k * 1024); } while (0)
; #define PG8_LDB(dst, b, h) do { _Pragma("unroll") for (int n = 0; n < 2; ++n) _Pragma("unroll") for (int k = 0; k < 2; ++k) dst[n][k] = *(const PG8_LAS bf16x8*)(lds + PG8_SB(b, h) + boff + n * 2048 + k * 1024); } while (0)
; #define PG8_MMA(ai, bj, At, Bt) do { __builtin_amdgcn_s_setprio(1); _Pragma("unroll") for (int m = 0; m < 4; ++m) _Pragma("unroll") for (int n = 0; n < 2; ++n) _Pragma("unroll") for (int k = 0; k < 2; ++k) \
;         acc[ai][bj][m][n] = __builtin_amdgcn_mfma_f32_16x16x32_bf16(Bt[n][k], At[m][k], acc[ai][bj][m][n], 0, 0, 0); __builtin_amdgcn_s_setprio(0); } while (0)
; #define PG8_WAIT_V(n) asm volatile("s_waitcnt vmcnt(" #n ")" ::: "memory")
; #define PG8_WAIT_L(n) asm volatile("s_waitcnt lgkmcnt(" #n ")" ::: "memory")
; #define PG8_BAR __builtin_amdgcn_s_barrier()
; #define PG8_SCHED __builtin_amdgcn_sched_barrier(0)
; template <class Epi, class Sched, bool ALIGN_EPI = false, bool SP2 = false>
; __device__ __forceinline__ void gemm_phase(PG8_LAS unsigned char* lds, const Gemm g, const Sched& S, const Epi& E) {
;     ...
;             PG8_LDB(B0, 0, 0); PG8_LDB(B1, 0, 1); PG8_SCHED; PG8_LDA(At, 0, 0); PG8_STAGE(PG8_SA(1, 1), a1 + hstep, voffA);
;             PG8_WAIT_V(8); PG8_WAIT_L(0); PG8_BAR; PG8_MMA(0, 0, At, B0); PG8_MMA(0, 1, At, B1); PG8_BAR; PG8_SCHED;
;             PG8_LDA(At, 0, 1); PG8_STAGE(PG8_SB(0, 0), b2, voffB); PG8_STAGE(PG8_SB(0, 1), b2 + hstep, voffB); PG8_STAGE(PG8_SA(0, 0), a2, voffA);
;             PG8_WAIT_V(8); PG8_WAIT_L(0); PG8_BAR; PG8_MMA(1, 0, At, B0); PG8_MMA(1, 1, At, B1); PG8_BAR; PG8_SCHED;
.LBB0_480:
	s_setprio 1
	s_add_u32 s8, s26, 0x100
	s_addc_u32 s9, s27, 0
	s_add_i32 s54, 0, 0x10000
	s_cmp_eq_u32 s53, 40
	s_cselect_b32 s31, s23, s9
	s_cselect_b32 s30, s22, s8
	s_cselect_b32 s29, s25, s45
	s_cselect_b32 s28, s24, s44
	s_add_i32 s55, 0, 0x14000
	v_add_u32_e32 v100, s54, v234
	v_add_u32_e32 v144, s55, v234
	ds_read_b128 v[68:71], v100
	ds_read_b128 v[80:83], v100 offset:1024
	ds_read_b128 v[92:95], v100 offset:2048
	ds_read_b128 v[100:103], v100 offset:3072
	ds_read_b128 v[112:115], v144
	ds_read_b128 v[120:123], v144 offset:1024
	ds_read_b128 v[132:135], v144 offset:2048
	ds_read_b128 v[144:147], v144 offset:3072
	v_lshl_add_u64 v[198:199], s[26:27], 0, v[204:205]
	s_add_i32 m0, s40, 0xc000
	ds_read_b128 v[156:159], v236
	ds_read_b128 v[168:171], v236 offset:1024
	ds_read_b128 v[172:175], v236 offset:2048
	ds_read_b128 v[176:179], v236 offset:3072
	ds_read_b128 v[180:183], v236 offset:4096
	ds_read_b128 v[184:187], v236 offset:5120
	ds_read_b128 v[188:191], v236 offset:6144
	ds_read_b128 v[208:211], v236 offset:7168
	global_load_lds_dwordx4 v[198:199], off
	v_lshl_add_u64 v[198:199], s[26:27], 0, v[206:207]
	s_add_i32 m0, s40, 0xe000
	s_nop 0
	global_load_lds_dwordx4 v[198:199], off
	s_waitcnt vmcnt(8)
	s_waitcnt lgkmcnt(0)
	s_setprio 0
	s_barrier
	s_waitcnt lgkmcnt(0)
	v_mfma_f32_16x16x32_bf16 v[164:167], v[68:71], v[156:159], v[164:167]
	v_mfma_f32_16x16x32_bf16 v[160:163], v[92:95], v[156:159], v[160:163]
	v_mfma_f32_16x16x32_bf16 v[140:143], v[68:71], v[172:175], v[140:143]
	v_mfma_f32_16x16x32_bf16 v[136:139], v[92:95], v[172:175], v[136:139]
	v_mfma_f32_16x16x32_bf16 v[116:119], v[68:71], v[180:183], v[116:119]
	v_mfma_f32_16x16x32_bf16 v[108:111], v[92:95], v[180:183], v[108:111]
	v_mfma_f32_16x16x32_bf16 v[88:91], v[68:71], v[188:191], v[88:91]
	v_mfma_f32_16x16x32_bf16 v[84:87], v[92:95], v[188:191], v[84:87]
	v_mfma_f32_16x16x32_bf16 v[164:167], v[80:83], v[168:171], v[164:167]
	v_mfma_f32_16x16x32_bf16 v[160:163], v[100:103], v[168:171], v[160:163]
	v_mfma_f32_16x16x32_bf16 v[140:143], v[80:83], v[176:179], v[140:143]
	v_mfma_f32_16x16x32_bf16 v[136:139], v[100:103], v[176:179], v[136:139]
	v_mfma_f32_16x16x32_bf16 v[116:119], v[80:83], v[184:187], v[116:119]
	v_mfma_f32_16x16x32_bf16 v[108:111], v[100:103], v[184:187], v[108:111]
	v_mfma_f32_16x16x32_bf16 v[88:91], v[80:83], v[208:211], v[88:91]
	v_mfma_f32_16x16x32_bf16 v[84:87], v[100:103], v[208:211], v[84:87]
	v_mfma_f32_16x16x32_bf16 v[152:155], v[112:115], v[156:159], v[152:155]
	v_mfma_f32_16x16x32_bf16 v[148:151], v[132:135], v[156:159], v[148:151]
	v_mfma_f32_16x16x32_bf16 v[128:131], v[112:115], v[172:175], v[128:131]
	v_mfma_f32_16x16x32_bf16 v[124:127], v[132:135], v[172:175], v[124:127]
	v_mfma_f32_16x16x32_bf16 v[104:107], v[112:115], v[180:183], v[104:107]
	v_mfma_f32_16x16x32_bf16 v[96:99], v[132:135], v[180:183], v[96:99]
	v_mfma_f32_16x16x32_bf16 v[76:79], v[112:115], v[188:191], v[76:79]
	v_mfma_f32_16x16x32_bf16 v[72:75], v[132:135], v[188:191], v[72:75]
	v_mfma_f32_16x16x32_bf16 v[152:155], v[120:123], v[168:171], v[152:155]
	v_mfma_f32_16x16x32_bf16 v[148:151], v[144:147], v[168:171], v[148:151]
	v_mfma_f32_16x16x32_bf16 v[128:131], v[120:123], v[176:179], v[128:131]
	v_mfma_f32_16x16x32_bf16 v[124:127], v[144:147], v[176:179], v[124:127]
	v_mfma_f32_16x16x32_bf16 v[104:107], v[120:123], v[184:187], v[104:107]
	v_mfma_f32_16x16x32_bf16 v[96:99], v[144:147], v[184:187], v[96:99]
	v_mfma_f32_16x16x32_bf16 v[76:79], v[120:123], v[208:211], v[76:79]
	v_mfma_f32_16x16x32_bf16 v[72:75], v[144:147], v[208:211], v[72:75]
	s_barrier
	s_setprio 1
	s_add_i32 s26, s54, s39
	v_lshl_add_u64 v[198:199], s[28:29], 0, v[192:193]
	s_mov_b32 m0, s26
	ds_read_b128 v[156:159], v236 offset:16384
	ds_read_b128 v[168:171], v236 offset:17408
	ds_read_b128 v[172:175], v236 offset:18432
	ds_read_b128 v[176:179], v236 offset:19456
	ds_read_b128 v[180:183], v236 offset:20480
	ds_read_b128 v[184:187], v236 offset:21504
	ds_read_b128 v[188:191], v236 offset:22528
	ds_read_b128 v[208:211], v236 offset:23552
	global_load_lds_dwordx4 v[198:199], off
	s_add_i32 m0, s26, 0x2000
	s_add_u32 s26, s28, 0xb0000
	v_lshl_add_u64 v[212:213], s[28:29], 0, v[202:203]
	s_addc_u32 s27, s29, 0
	s_add_i32 s54, s55, s39
	global_load_lds_dwordx4 v[212:213], off
	v_lshl_add_u64 v[214:215], s[26:27], 0, v[192:193]
	s_mov_b32 m0, s54
	v_lshl_add_u64 v[216:217], s[30:31], 0, v[194:195]
	global_load_lds_dwordx4 v[214:215], off
	v_lshl_add_u64 v[214:215], s[26:27], 0, v[202:203]
	s_add_i32 m0, s54, 0x2000
	s_nop 0
	global_load_lds_dwordx4 v[214:215], off
	v_lshl_add_u64 v[214:215], s[30:31], 0, v[0:1]
	s_mov_b32 m0, s40
	s_nop 0
	global_load_lds_dwordx4 v[214:215], off
	s_mov_b32 m0, s41
	s_nop 0
	global_load_lds_dwordx4 v[216:217], off
	s_waitcnt vmcnt(8)
	s_waitcnt lgkmcnt(0)
	s_setprio 0
	s_barrier
; #define PG8_STAGE(bufoff, gbase, voff) do { _Pragma("unroll") for (int _i = 0; _i < 2; ++_i) \
;         __builtin_amdgcn_global_load_lds((const unsigned*)((const char*)(gbase) + (voff)[_i]), (PG8_LAS unsigned*)(lds + (bufoff) + ldsw + _i * 8192), 16, 0, 0); } while (0)
; #define PG8_LDA(dst, b, h) do { _Pragma("unroll") for (int m = 0; m < 4; ++m) _Pragma("unroll") for (int k = 0; k < 2; ++k) dst[m][k] = *(const PG8_LAS bf16x8*)(lds + PG8_SA(b, h) + aoff + m * 2048 + k * 1024); } while (0)
; #define PG8_LDB(dst, b, h) do { _Pragma("unroll") for (int n = 0; n < 2; ++n) _Pragma("unroll") for (int k = 0; k < 2; ++k) dst[n][k] = *(const PG8_LAS bf16x8*)(lds + PG8_SB(b, h) + boff + n * 2048 + k * 1024); } while (0)
; #define PG8_MMA(ai, bj, At, Bt) do { __builtin_amdgcn_s_setprio(1); _Pragma("unroll") for (int m = 0; m < 4; ++m) _Pragma("unroll") for (int n = 0; n < 2; ++n) _Pragma("unroll") for (int k = 0; k < 2; ++k) \
;         acc[ai][bj][m][n] = __builtin_amdgcn_mfma_f32_16x16x32_bf16(Bt[n][k], At[m][k], acc[ai][bj][m][n], 0, 0, 0); __builtin_amdgcn_s_setprio(0); } while (0)
; #define PG8_WAIT_V(n) asm volatile("s_waitcnt vmcnt(" #n ")" ::: "memory")
; #define PG8_WAIT_L(n) asm volatile("s_waitcnt lgkmcnt(" #n ")" ::: "memory")
; #define PG8_BAR __builtin_amdgcn_s_barrier()
; #define PG8_SCHED __builtin_amdgcn_sched_barrier(0)
; template <class Epi, class Sched, bool ALIGN_EPI = false, bool SP2 = false>
; __device__ __forceinline__ void gemm_phase(PG8_LAS unsigned char* lds, const Gemm g, const Sched& S, const Epi& E) {
;     ...
;             PG8_WAIT_V(8); PG8_WAIT_L(0); PG8_BAR; PG8_MMA(1, 0, At, B0); PG8_MMA(1, 1, At, B1); PG8_BAR; PG8_SCHED;
;             PG8_LDB(B0, 1, 0); PG8_LDB(B1, 1, 1); PG8_SCHED; PG8_LDA(At, 1, 0); PG8_STAGE(PG8_SA(0, 1), a2 + hstep, voffA);
;             PG8_WAIT_V(8); PG8_WAIT_L(0); PG8_BAR; PG8_MMA(0, 0, At, B0); PG8_MMA(0, 1, At, B1); PG8_BAR; PG8_SCHED;
	s_waitcnt lgkmcnt(0)
	v_mfma_f32_16x16x32_bf16 v[64:67], v[68:71], v[156:159], v[64:67]
	v_mfma_f32_16x16x32_bf16 v[60:63], v[92:95], v[156:159], v[60:63]
	v_mfma_f32_16x16x32_bf16 v[48:51], v[68:71], v[172:175], v[48:51]
	v_mfma_f32_16x16x32_bf16 v[44:47], v[92:95], v[172:175], v[44:47]
	v_mfma_f32_16x16x32_bf16 v[32:35], v[68:71], v[180:183], v[32:35]
	v_mfma_f32_16x16x32_bf16 v[28:31], v[92:95], v[180:183], v[28:31]
	v_mfma_f32_16x16x32_bf16 v[16:19], v[68:71], v[188:191], v[16:19]
	v_mfma_f32_16x16x32_bf16 v[12:15], v[92:95], v[188:191], v[12:15]
	v_mfma_f32_16x16x32_bf16 v[64:67], v[80:83], v[168:171], v[64:67]
	v_mfma_f32_16x16x32_bf16 v[60:63], v[100:103], v[168:171], v[60:63]
	v_mfma_f32_16x16x32_bf16 v[48:51], v[80:83], v[176:179], v[48:51]
	v_mfma_f32_16x16x32_bf16 v[44:47], v[100:103], v[176:179], v[44:47]
	v_mfma_f32_16x16x32_bf16 v[32:35], v[80:83], v[184:187], v[32:35]
	v_mfma_f32_16x16x32_bf16 v[28:31], v[100:103], v[184:187], v[28:31]
	v_mfma_f32_16x16x32_bf16 v[16:19], v[80:83], v[208:211], v[16:19]
	v_mfma_f32_16x16x32_bf16 v[12:15], v[100:103], v[208:211], v[12:15]
	v_mfma_f32_16x16x32_bf16 v[56:59], v[112:115], v[156:159], v[56:59]
	v_mfma_f32_16x16x32_bf16 v[52:55], v[132:135], v[156:159], v[52:55]
	v_mfma_f32_16x16x32_bf16 v[40:43], v[112:115], v[172:175], v[40:43]
	v_mfma_f32_16x16x32_bf16 v[36:39], v[132:135], v[172:175], v[36:39]
	v_mfma_f32_16x16x32_bf16 v[24:27], v[112:115], v[180:183], v[24:27]
	v_mfma_f32_16x16x32_bf16 v[20:23], v[132:135], v[180:183], v[20:23]
	v_mfma_f32_16x16x32_bf16 v[8:11], v[112:115], v[188:191], v[8:11]
	v_mfma_f32_16x16x32_bf16 v[4:7], v[132:135], v[188:191], v[4:7]
	v_mfma_f32_16x16x32_bf16 v[56:59], v[120:123], v[168:171], v[56:59]
	v_mfma_f32_16x16x32_bf16 v[52:55], v[144:147], v[168:171], v[52:55]
	v_mfma_f32_16x16x32_bf16 v[40:43], v[120:123], v[176:179], v[40:43]
	v_mfma_f32_16x16x32_bf16 v[36:39], v[144:147], v[176:179], v[36:39]
	v_mfma_f32_16x16x32_bf16 v[24:27], v[120:123], v[184:187], v[24:27]
	v_mfma_f32_16x16x32_bf16 v[20:23], v[144:147], v[184:187], v[20:23]
	v_mfma_f32_16x16x32_bf16 v[8:11], v[120:123], v[208:211], v[8:11]
	v_mfma_f32_16x16x32_bf16 v[4:7], v[144:147], v[208:211], v[4:7]
	s_barrier
	s_setprio 1
	s_add_i32 s54, 0, 0x18000
	s_add_i32 s55, 0, 0x1c000
	v_add_u32_e32 v100, s54, v234
	v_add_u32_e32 v144, s55, v234
	ds_read_b128 v[68:71], v100
	ds_read_b128 v[80:83], v100 offset:1024
	ds_read_b128 v[92:95], v100 offset:2048
	ds_read_b128 v[100:103], v100 offset:3072
	ds_read_b128 v[112:115], v144
	ds_read_b128 v[120:123], v144 offset:1024
	ds_read_b128 v[132:135], v144 offset:2048
	ds_read_b128 v[144:147], v144 offset:3072
	s_add_u32 s26, s30, 0xb0000
	s_addc_u32 s27, s31, 0
	s_mov_b32 m0, s42
	v_lshl_add_u64 v[218:219], s[26:27], 0, v[0:1]
	ds_read_b128 v[156:159], v236 offset:32768
	ds_read_b128 v[168:171], v236 offset:33792
	ds_read_b128 v[172:175], v236 offset:34816
	ds_read_b128 v[176:179], v236 offset:35840
	ds_read_b128 v[180:183], v236 offset:36864
	ds_read_b128 v[184:187], v236 offset:37888
	ds_read_b128 v[188:191], v236 offset:38912
	ds_read_b128 v[208:211], v236 offset:39936
	global_load_lds_dwordx4 v[218:219], off
	v_lshl_add_u64 v[218:219], s[26:27], 0, v[194:195]
	s_mov_b32 m0, s43
	s_nop 0
	global_load_lds_dwordx4 v[218:219], off
	s_waitcnt vmcnt(8)
	s_waitcnt lgkmcnt(0)
	s_setprio 0
	s_barrier
	s_waitcnt lgkmcnt(0)
	v_mfma_f32_16x16x32_bf16 v[164:167], v[68:71], v[156:159], v[164:167]
	v_mfma_f32_16x16x32_bf16 v[160:163], v[92:95], v[156:159], v[160:163]
	v_mfma_f32_16x16x32_bf16 v[140:143], v[68:71], v[172:175], v[140:143]
	v_mfma_f32_16x16x32_bf16 v[136:139], v[92:95], v[172:175], v[136:139]
	v_mfma_f32_16x16x32_bf16 v[116:119], v[68:71], v[180:183], v[116:119]
	v_mfma_f32_16x16x32_bf16 v[108:111], v[92:95], v[180:183], v[108:111]
	v_mfma_f32_16x16x32_bf16 v[88:91], v[68:71], v[188:191], v[88:91]
	v_mfma_f32_16x16x32_bf16 v[84:87], v[92:95], v[188:191], v[84:87]
	v_mfma_f32_16x16x32_bf16 v[164:167], v[80:83], v[168:171], v[164:167]
	v_mfma_f32_16x16x32_bf16 v[160:163], v[100:103], v[168:171], v[160:163]
	v_mfma_f32_16x16x32_bf16 v[140:143], v[80:83], v[176:179], v[140:143]
	v_mfma_f32_16x16x32_bf16 v[136:139], v[100:103], v[176:179], v[136:139]
	v_mfma_f32_16x16x32_bf16 v[116:119], v[80:83], v[184:187], v[116:119]
	v_mfma_f32_16x16x32_bf16 v[108:111], v[100:103], v[184:187], v[108:111]
	v_mfma_f32_16x16x32_bf16 v[88:91], v[80:83], v[208:211], v[88:91]
	v_mfma_f32_16x16x32_bf16 v[84:87], v[100:103], v[208:211], v[84:87]
	v_mfma_f32_16x16x32_bf16 v[152:155], v[112:115], v[156:159], v[152:155]
	v_mfma_f32_16x16x32_bf16 v[148:151], v[132:135], v[156:159], v[148:151]
	v_mfma_f32_16x16x32_bf16 v[128:131], v[112:115], v[172:175], v[128:131]
	v_mfma_f32_16x16x32_bf16 v[124:127], v[132:135], v[172:175], v[124:127]
	v_mfma_f32_16x16x32_bf16 v[104:107], v[112:115], v[180:183], v[104:107]
	v_mfma_f32_16x16x32_bf16 v[96:99], v[132:135], v[180:183], v[96:99]
	v_mfma_f32_16x16x32_bf16 v[76:79], v[112:115], v[188:191], v[76:79]
	v_mfma_f32_16x16x32_bf16 v[72:75], v[132:135], v[188:191], v[72:75]
	v_mfma_f32_16x16x32_bf16 v[152:155], v[120:123], v[168:171], v[152:155]
	v_mfma_f32_16x16x32_bf16 v[148:151], v[144:147], v[168:171], v[148:151]
	v_mfma_f32_16x16x32_bf16 v[128:131], v[120:123], v[176:179], v[128:131]
	v_mfma_f32_16x16x32_bf16 v[124:127], v[144:147], v[176:179], v[124:127]
	v_mfma_f32_16x16x32_bf16 v[104:107], v[120:123], v[184:187], v[104:107]
	v_mfma_f32_16x16x32_bf16 v[96:99], v[144:147], v[184:187], v[96:99]
	v_mfma_f32_16x16x32_bf16 v[76:79], v[120:123], v[208:211], v[76:79]
	v_mfma_f32_16x16x32_bf16 v[72:75], v[144:147], v[208:211], v[72:75]
	s_barrier
; #define PG8_STAGE(bufoff, gbase, voff) do { _Pragma("unroll") for (int _i = 0; _i < 2; ++_i) \
;         __builtin_amdgcn_global_load_lds((const unsigned*)((const char*)(gbase) + (voff)[_i]), (PG8_LAS unsigned*)(lds + (bufoff) + ldsw + _i * 8192), 16, 0, 0); } while (0)
; #define PG8_LDA(dst, b, h) do { _Pragma("unroll") for (int m = 0; m < 4; ++m) _Pragma("unroll") for (int k = 0; k < 2; ++k) dst[m][k] = *(const PG8_LAS bf16x8*)(lds + PG8_SA(b, h) + aoff + m * 2048 + k * 1024); } while (0)
; #define PG8_MMA(ai, bj, At, Bt) do { __builtin_amdgcn_s_setprio(1); _Pragma("unroll") for (int m = 0; m < 4; ++m) _Pragma("unroll") for (int n = 0; n < 2; ++n) _Pragma("unroll") for (int k = 0; k < 2; ++k) \
;         acc[ai][bj][m][n] = __builtin_amdgcn_mfma_f32_16x16x32_bf16(Bt[n][k], At[m][k], acc[ai][bj][m][n], 0, 0, 0); __builtin_amdgcn_s_setprio(0); } while (0)
; #define PG8_WAIT_V(n) asm volatile("s_waitcnt vmcnt(" #n ")" ::: "memory")
; #define PG8_WAIT_L(n) asm volatile("s_waitcnt lgkmcnt(" #n ")" ::: "memory")
; #define PG8_BAR __builtin_amdgcn_s_barrier()
; #define PG8_SCHED __builtin_amdgcn_sched_barrier(0)
; template <class Epi, class Sched, bool ALIGN_EPI = false, bool SP2 = false>
; __device__ __forceinline__ void gemm_phase(PG8_LAS unsigned char* lds, const Gemm g, const Sched& S, const Epi& E) {
;     ...
;         for (int t = 0; t < nt; t += 2) {
;     ...
;             PG8_LDA(At, 1, 1); PG8_STAGE(PG8_SB(1, 0), b3, voffB); PG8_STAGE(PG8_SB(1, 1), b3 + hstep, voffB); PG8_STAGE(PG8_SA(1, 0), a3, voffA);
;             PG8_WAIT_V(8); PG8_WAIT_L(0); PG8_BAR; PG8_MMA(1, 0, At, B0); PG8_MMA(1, 1, At, B1); PG8_BAR; PG8_SCHED;
	s_setprio 1
	s_add_i32 s26, s54, s39
	v_lshl_add_u64 v[198:199], v[198:199], 0, s[82:83]
	s_mov_b32 m0, s26
	ds_read_b128 v[156:159], v236 offset:49152
	ds_read_b128 v[168:171], v236 offset:50176
	ds_read_b128 v[172:175], v236 offset:51200
	ds_read_b128 v[176:179], v236 offset:52224
	ds_read_b128 v[180:183], v236 offset:53248
	ds_read_b128 v[184:187], v236 offset:54272
	ds_read_b128 v[188:191], v236 offset:55296
	ds_read_b128 v[208:211], v236 offset:56320
	global_load_lds_dwordx4 v[198:199], off
	s_add_i32 m0, s26, 0x2000
	s_add_u32 s26, s28, 0xb0080
	v_lshl_add_u64 v[198:199], v[212:213], 0, s[82:83]
	s_addc_u32 s27, s29, 0
	s_add_i32 s28, s55, s39
	global_load_lds_dwordx4 v[198:199], off
	v_lshl_add_u64 v[198:199], s[26:27], 0, v[192:193]
	s_mov_b32 m0, s28
	s_nop 0
	global_load_lds_dwordx4 v[198:199], off
	v_lshl_add_u64 v[198:199], s[26:27], 0, v[202:203]
	s_add_i32 m0, s28, 0x2000
	s_nop 0
	global_load_lds_dwordx4 v[198:199], off
	v_lshl_add_u64 v[198:199], v[214:215], 0, s[82:83]
	s_mov_b32 m0, s47
	s_nop 0
	global_load_lds_dwordx4 v[198:199], off
	v_lshl_add_u64 v[198:199], v[216:217], 0, s[82:83]
	s_mov_b32 m0, s48
	s_nop 0
	global_load_lds_dwordx4 v[198:199], off
	s_waitcnt vmcnt(8)
	s_waitcnt lgkmcnt(0)
	s_setprio 0
	s_barrier
	s_waitcnt lgkmcnt(0)
	v_mfma_f32_16x16x32_bf16 v[64:67], v[68:71], v[156:159], v[64:67]
	v_mfma_f32_16x16x32_bf16 v[60:63], v[92:95], v[156:159], v[60:63]
	v_mfma_f32_16x16x32_bf16 v[48:51], v[68:71], v[172:175], v[48:51]
	v_mfma_f32_16x16x32_bf16 v[44:47], v[92:95], v[172:175], v[44:47]
	v_mfma_f32_16x16x32_bf16 v[32:35], v[68:71], v[180:183], v[32:35]
	v_mfma_f32_16x16x32_bf16 v[28:31], v[92:95], v[180:183], v[28:31]
	v_mfma_f32_16x16x32_bf16 v[16:19], v[68:71], v[188:191], v[16:19]
	v_mfma_f32_16x16x32_bf16 v[12:15], v[92:95], v[188:191], v[12:15]
	v_mfma_f32_16x16x32_bf16 v[64:67], v[80:83], v[168:171], v[64:67]
	v_mfma_f32_16x16x32_bf16 v[60:63], v[100:103], v[168:171], v[60:63]
	v_mfma_f32_16x16x32_bf16 v[48:51], v[80:83], v[176:179], v[48:51]
	v_mfma_f32_16x16x32_bf16 v[44:47], v[100:103], v[176:179], v[44:47]
	v_mfma_f32_16x16x32_bf16 v[32:35], v[80:83], v[184:187], v[32:35]
	v_mfma_f32_16x16x32_bf16 v[28:31], v[100:103], v[184:187], v[28:31]
	v_mfma_f32_16x16x32_bf16 v[16:19], v[80:83], v[208:211], v[16:19]
	v_mfma_f32_16x16x32_bf16 v[12:15], v[100:103], v[208:211], v[12:15]
	v_mfma_f32_16x16x32_bf16 v[56:59], v[112:115], v[156:159], v[56:59]
	v_mfma_f32_16x16x32_bf16 v[52:55], v[132:135], v[156:159], v[52:55]
	v_mfma_f32_16x16x32_bf16 v[40:43], v[112:115], v[172:175], v[40:43]
	v_mfma_f32_16x16x32_bf16 v[36:39], v[132:135], v[172:175], v[36:39]
	v_mfma_f32_16x16x32_bf16 v[24:27], v[112:115], v[180:183], v[24:27]
	v_mfma_f32_16x16x32_bf16 v[20:23], v[132:135], v[180:183], v[20:23]
	v_mfma_f32_16x16x32_bf16 v[8:11], v[112:115], v[188:191], v[8:11]
	v_mfma_f32_16x16x32_bf16 v[4:7], v[132:135], v[188:191], v[4:7]
	v_mfma_f32_16x16x32_bf16 v[56:59], v[120:123], v[168:171], v[56:59]
	v_mfma_f32_16x16x32_bf16 v[52:55], v[144:147], v[168:171], v[52:55]
	v_mfma_f32_16x16x32_bf16 v[40:43], v[120:123], v[176:179], v[40:43]
	v_mfma_f32_16x16x32_bf16 v[36:39], v[144:147], v[176:179], v[36:39]
	v_mfma_f32_16x16x32_bf16 v[24:27], v[120:123], v[184:187], v[24:27]
	v_mfma_f32_16x16x32_bf16 v[20:23], v[144:147], v[184:187], v[20:23]
	v_mfma_f32_16x16x32_bf16 v[8:11], v[120:123], v[208:211], v[8:11]
	v_mfma_f32_16x16x32_bf16 v[4:7], v[144:147], v[208:211], v[4:7]
	s_barrier
	s_setprio 1
	s_add_i32 s53, s53, 2
	s_add_u32 s44, s44, 0x100
	s_addc_u32 s45, s45, 0
	s_cmp_gt_u32 s53, 41
	s_mov_b64 s[26:27], s[8:9]
	s_cbranch_scc0 .LBB0_480
	s_setprio 0
	s_and_b64 vcc, exec, s[20:21]
	s_cbranch_vccz .LBB0_483
	s_barrier
